# v082 + FFN-in and W_in GEMMs: the barrier pair that aligns the two wave halves' epilogues dropped between units (kept before the last unit) so the leading half's epilogue overlaps the other half's las
# baseline (speedup 1.0000x reference)
; #define PG8_STAGE(bufoff, gbase, voff) do { _Pragma("unroll") for (int _i = 0; _i < 2; ++_i) \
;         __builtin_amdgcn_global_load_lds((const gunsigned*)((const gchar*)(gbase) + (voff)[_i]), (LAS unsigned*)(lds + (bufoff) + ldsw + _i * 8192), 16, 0, 0); } while (0)
; #define PG8_LDA(dst, b, h) do { _Pragma("unroll") for (int m = 0; m < 4; ++m) _Pragma("unroll") for (int k = 0; k < 2; ++k) dst[m][k] = *(const LAS bf16x8*)(lds + PG8_SA(b, h) + aoff + m * 2048 + k * 1024); } while (0)
; #define PG8_LDB(dst, b, h) do { _Pragma("unroll") for (int n = 0; n < 2; ++n) _Pragma("unroll") for (int k = 0; k < 2; ++k) dst[n][k] = *(const LAS bf16x8*)(lds + PG8_SB(b, h) + boff + n * 2048 + k * 1024); } while (0)
; #define PG8_MMA(ai, bj, At, Bt) do { __builtin_amdgcn_s_setprio(1); _Pragma("unroll") for (int m = 0; m < 4; ++m) _Pragma("unroll") for (int n = 0; n < 2; ++n) _Pragma("unroll") for (int k = 0; k < 2; ++k) \
;         acc[ai][bj][m][n] = __builtin_amdgcn_mfma_f32_16x16x32_bf16(Bt[n][k], At[m][k], acc[ai][bj][m][n], 0, 0, 0); __builtin_amdgcn_s_setprio(0); } while (0)
; #define PG8_WAIT_V(n) asm volatile("s_waitcnt vmcnt(" #n ")" ::: "memory")
; #define PG8_WAIT_L(n) asm volatile("s_waitcnt lgkmcnt(" #n ")" ::: "memory")
; #define PG8_BAR __builtin_amdgcn_s_barrier()
; #define PG8_SCHED __builtin_amdgcn_sched_barrier(0)
; template <class Epi, class Sched>
; __device__ __forceinline__ void gemm_phase(LAS unsigned char* lds, const int tid, const Gemm g, const Sched& S, const Epi& E) {
;     ...
;             PG8_LDB(B0, 0, 0); PG8_LDB(B1, 0, 1); PG8_SCHED; PG8_LDA(At, 0, 0); PG8_STAGE(PG8_SA(1, 1), a1 + hstep, voffA);
;             PG8_WAIT_V(8); PG8_WAIT_L(0); PG8_BAR; PG8_MMA(0, 0, At, B0); PG8_MMA(0, 1, At, B1); PG8_BAR; PG8_SCHED;
;             PG8_LDA(At, 0, 1); PG8_STAGE(PG8_SB(0, 0), b2, voffB); PG8_STAGE(PG8_SB(0, 1), b2 + hstep, voffB); PG8_STAGE(PG8_SA(0, 0), a2, voffA);
;             PG8_WAIT_V(8); PG8_WAIT_L(0); PG8_BAR; PG8_MMA(1, 0, At, B0); PG8_MMA(1, 1, At, B1); PG8_BAR; PG8_SCHED;
.LBB0_369:
	s_add_u32 s20, s16, 0xfffc0080
	s_addc_u32 s21, s17, -1
	s_add_i32 s29, 0, 0x10000
	s_cmp_eq_u32 s31, 12
	s_cselect_b32 s57, s11, s21
	s_cselect_b32 s56, s12, s20
	v_add_u32_e32 v140, s29, v145
	s_cselect_b32 s21, s9, s24
	s_cselect_b32 s20, s15, s23
	s_add_i32 s30, 0, 0x14000
	ds_read_b128 v[146:149], v140
	ds_read_b128 v[156:159], v140 offset:1024
	ds_read_b128 v[160:163], v140 offset:2048
	ds_read_b128 v[164:167], v140 offset:3072
	v_add_u32_e32 v140, s30, v145
	ds_read_b128 v[168:171], v140
	ds_read_b128 v[172:175], v140 offset:1024
	ds_read_b128 v[176:179], v140 offset:2048
	ds_read_b128 v[180:183], v140 offset:3072
	s_add_i32 m0, s73, 0xc000
	ds_read_b128 v[184:187], v155
	ds_read_b128 v[188:191], v155 offset:1024
	ds_read_b128 v[192:195], v155 offset:2048
	ds_read_b128 v[204:207], v155 offset:3072
	ds_read_b128 v[208:211], v155 offset:4096
	ds_read_b128 v[212:215], v155 offset:5120
	ds_read_b128 v[216:219], v155 offset:6144
	ds_read_b128 v[220:223], v155 offset:7168
	global_load_lds_dwordx4 v138, s[16:17]
	s_add_i32 m0, s73, 0xe000
	s_nop 0
	global_load_lds_dwordx4 v136, s[16:17]
	s_waitcnt vmcnt(8)
	s_waitcnt lgkmcnt(0)
	s_setprio 1
	s_barrier
	v_mfma_f32_16x16x32_bf16 v[126:129], v[146:149], v[184:187], v[126:129]
	v_mfma_f32_16x16x32_bf16 v[118:121], v[160:163], v[184:187], v[118:121]
	v_mfma_f32_16x16x32_bf16 v[110:113], v[146:149], v[192:195], v[110:113]
	v_mfma_f32_16x16x32_bf16 v[102:105], v[160:163], v[192:195], v[102:105]
	v_mfma_f32_16x16x32_bf16 v[94:97], v[146:149], v[208:211], v[94:97]
	v_mfma_f32_16x16x32_bf16 v[86:89], v[160:163], v[208:211], v[86:89]
	v_mfma_f32_16x16x32_bf16 v[78:81], v[146:149], v[216:219], v[78:81]
	v_mfma_f32_16x16x32_bf16 v[70:73], v[160:163], v[216:219], v[70:73]
	v_mfma_f32_16x16x32_bf16 v[126:129], v[156:159], v[188:191], v[126:129]
	v_mfma_f32_16x16x32_bf16 v[118:121], v[164:167], v[188:191], v[118:121]
	v_mfma_f32_16x16x32_bf16 v[110:113], v[156:159], v[204:207], v[110:113]
	v_mfma_f32_16x16x32_bf16 v[102:105], v[164:167], v[204:207], v[102:105]
	v_mfma_f32_16x16x32_bf16 v[94:97], v[156:159], v[212:215], v[94:97]
	v_mfma_f32_16x16x32_bf16 v[86:89], v[164:167], v[212:215], v[86:89]
	v_mfma_f32_16x16x32_bf16 v[78:81], v[156:159], v[220:223], v[78:81]
	v_mfma_f32_16x16x32_bf16 v[70:73], v[164:167], v[220:223], v[70:73]
	s_setprio 0
	s_setprio 1
	v_mfma_f32_16x16x32_bf16 v[122:125], v[168:171], v[184:187], v[122:125]
	v_mfma_f32_16x16x32_bf16 v[114:117], v[176:179], v[184:187], v[114:117]
	v_mfma_f32_16x16x32_bf16 v[106:109], v[168:171], v[192:195], v[106:109]
	v_mfma_f32_16x16x32_bf16 v[98:101], v[176:179], v[192:195], v[98:101]
	v_mfma_f32_16x16x32_bf16 v[90:93], v[168:171], v[208:211], v[90:93]
	v_mfma_f32_16x16x32_bf16 v[82:85], v[176:179], v[208:211], v[82:85]
	v_mfma_f32_16x16x32_bf16 v[74:77], v[168:171], v[216:219], v[74:77]
	v_mfma_f32_16x16x32_bf16 v[66:69], v[176:179], v[216:219], v[66:69]
	v_mfma_f32_16x16x32_bf16 v[122:125], v[172:175], v[188:191], v[122:125]
	v_mfma_f32_16x16x32_bf16 v[114:117], v[180:183], v[188:191], v[114:117]
	v_mfma_f32_16x16x32_bf16 v[106:109], v[172:175], v[204:207], v[106:109]
	v_mfma_f32_16x16x32_bf16 v[98:101], v[180:183], v[204:207], v[98:101]
	v_mfma_f32_16x16x32_bf16 v[90:93], v[172:175], v[212:215], v[90:93]
	v_mfma_f32_16x16x32_bf16 v[82:85], v[180:183], v[212:215], v[82:85]
	v_mfma_f32_16x16x32_bf16 v[74:77], v[172:175], v[220:223], v[74:77]
	v_mfma_f32_16x16x32_bf16 v[66:69], v[180:183], v[220:223], v[66:69]
	s_barrier
	s_setprio 0
	s_add_i32 s29, s29, s43
	s_mov_b32 m0, s29
	ds_read_b128 v[184:187], v155 offset:16384
	ds_read_b128 v[188:191], v155 offset:17408
	ds_read_b128 v[192:195], v155 offset:18432
	ds_read_b128 v[204:207], v155 offset:19456
	ds_read_b128 v[208:211], v155 offset:20480
	ds_read_b128 v[212:215], v155 offset:21504
	ds_read_b128 v[216:219], v155 offset:22528
	ds_read_b128 v[220:223], v155 offset:23552
	global_load_lds_dwordx4 v0, s[20:21]
	s_add_i32 m0, s29, 0x2000
	s_add_u32 s46, s20, 0x40000
	s_addc_u32 s47, s21, 0
	s_add_i32 s29, s30, s43
	global_load_lds_dwordx4 v130, s[20:21]
	s_mov_b32 m0, s29
	s_nop 0
	global_load_lds_dwordx4 v0, s[46:47]
	s_add_i32 m0, s29, 0x2000
	s_nop 0
	global_load_lds_dwordx4 v130, s[46:47]
	s_mov_b32 m0, s73
	s_nop 0
	global_load_lds_dwordx4 v134, s[56:57]
	s_mov_b32 m0, s74
	s_nop 0
	global_load_lds_dwordx4 v132, s[56:57]
	s_waitcnt vmcnt(8)
	s_waitcnt lgkmcnt(0)
	s_setprio 1
	s_barrier
	v_mfma_f32_16x16x32_bf16 v[62:65], v[146:149], v[184:187], v[62:65]
	v_mfma_f32_16x16x32_bf16 v[54:57], v[160:163], v[184:187], v[54:57]
	v_mfma_f32_16x16x32_bf16 v[46:49], v[146:149], v[192:195], v[46:49]
	v_mfma_f32_16x16x32_bf16 v[38:41], v[160:163], v[192:195], v[38:41]
	v_mfma_f32_16x16x32_bf16 v[30:33], v[146:149], v[208:211], v[30:33]
	v_mfma_f32_16x16x32_bf16 v[22:25], v[160:163], v[208:211], v[22:25]
	v_mfma_f32_16x16x32_bf16 v[14:17], v[146:149], v[216:219], v[14:17]
	v_mfma_f32_16x16x32_bf16 v[6:9], v[160:163], v[216:219], v[6:9]
	v_mfma_f32_16x16x32_bf16 v[62:65], v[156:159], v[188:191], v[62:65]
	v_mfma_f32_16x16x32_bf16 v[54:57], v[164:167], v[188:191], v[54:57]
	v_mfma_f32_16x16x32_bf16 v[46:49], v[156:159], v[204:207], v[46:49]
	v_mfma_f32_16x16x32_bf16 v[38:41], v[164:167], v[204:207], v[38:41]
	v_mfma_f32_16x16x32_bf16 v[30:33], v[156:159], v[212:215], v[30:33]
	v_mfma_f32_16x16x32_bf16 v[22:25], v[164:167], v[212:215], v[22:25]
	v_mfma_f32_16x16x32_bf16 v[14:17], v[156:159], v[220:223], v[14:17]
	v_mfma_f32_16x16x32_bf16 v[6:9], v[164:167], v[220:223], v[6:9]
	s_setprio 0
	s_setprio 1
	v_mfma_f32_16x16x32_bf16 v[58:61], v[168:171], v[184:187], v[58:61]
	v_mfma_f32_16x16x32_bf16 v[50:53], v[176:179], v[184:187], v[50:53]
	v_mfma_f32_16x16x32_bf16 v[42:45], v[168:171], v[192:195], v[42:45]
	v_mfma_f32_16x16x32_bf16 v[34:37], v[176:179], v[192:195], v[34:37]
	v_mfma_f32_16x16x32_bf16 v[26:29], v[168:171], v[208:211], v[26:29]
	v_mfma_f32_16x16x32_bf16 v[18:21], v[176:179], v[208:211], v[18:21]
	v_mfma_f32_16x16x32_bf16 v[10:13], v[168:171], v[216:219], v[10:13]
	v_mfma_f32_16x16x32_bf16 v[2:5], v[176:179], v[216:219], v[2:5]
	v_mfma_f32_16x16x32_bf16 v[58:61], v[172:175], v[188:191], v[58:61]
	v_mfma_f32_16x16x32_bf16 v[50:53], v[180:183], v[188:191], v[50:53]
	v_mfma_f32_16x16x32_bf16 v[42:45], v[172:175], v[204:207], v[42:45]
	v_mfma_f32_16x16x32_bf16 v[34:37], v[180:183], v[204:207], v[34:37]
	v_mfma_f32_16x16x32_bf16 v[26:29], v[172:175], v[212:215], v[26:29]
	v_mfma_f32_16x16x32_bf16 v[18:21], v[180:183], v[212:215], v[18:21]
	v_mfma_f32_16x16x32_bf16 v[10:13], v[172:175], v[220:223], v[10:13]
	v_mfma_f32_16x16x32_bf16 v[2:5], v[180:183], v[220:223], v[2:5]
	s_barrier
; #define PG8_STAGE(bufoff, gbase, voff) do { _Pragma("unroll") for (int _i = 0; _i < 2; ++_i) \
;         __builtin_amdgcn_global_load_lds((const gunsigned*)((const gchar*)(gbase) + (voff)[_i]), (LAS unsigned*)(lds + (bufoff) + ldsw + _i * 8192), 16, 0, 0); } while (0)
; #define PG8_LDA(dst, b, h) do { _Pragma("unroll") for (int m = 0; m < 4; ++m) _Pragma("unroll") for (int k = 0; k < 2; ++k) dst[m][k] = *(const LAS bf16x8*)(lds + PG8_SA(b, h) + aoff + m * 2048 + k * 1024); } while (0)
; #define PG8_LDB(dst, b, h) do { _Pragma("unroll") for (int n = 0; n < 2; ++n) _Pragma("unroll") for (int k = 0; k < 2; ++k) dst[n][k] = *(const LAS bf16x8*)(lds + PG8_SB(b, h) + boff + n * 2048 + k * 1024); } while (0)
; #define PG8_MMA(ai, bj, At, Bt) do { __builtin_amdgcn_s_setprio(1); _Pragma("unroll") for (int m = 0; m < 4; ++m) _Pragma("unroll") for (int n = 0; n < 2; ++n) _Pragma("unroll") for (int k = 0; k < 2; ++k) \
;         acc[ai][bj][m][n] = __builtin_amdgcn_mfma_f32_16x16x32_bf16(Bt[n][k], At[m][k], acc[ai][bj][m][n], 0, 0, 0); __builtin_amdgcn_s_setprio(0); } while (0)
; #define PG8_WAIT_V(n) asm volatile("s_waitcnt vmcnt(" #n ")" ::: "memory")
; #define PG8_WAIT_L(n) asm volatile("s_waitcnt lgkmcnt(" #n ")" ::: "memory")
; #define PG8_BAR __builtin_amdgcn_s_barrier()
; #define PG8_SCHED __builtin_amdgcn_sched_barrier(0)
; template <class Epi, class Sched>
; __device__ __forceinline__ void gemm_phase(LAS unsigned char* lds, const int tid, const Gemm g, const Sched& S, const Epi& E) {
;     ...
;             PG8_LDB(B0, 1, 0); PG8_LDB(B1, 1, 1); PG8_SCHED; PG8_LDA(At, 1, 0); PG8_STAGE(PG8_SA(0, 1), a2 + hstep, voffA);
;             PG8_WAIT_V(8); PG8_WAIT_L(0); PG8_BAR; PG8_MMA(0, 0, At, B0); PG8_MMA(0, 1, At, B1); PG8_BAR; PG8_SCHED;
;             PG8_LDA(At, 1, 1); PG8_STAGE(PG8_SB(1, 0), b3, voffB); PG8_STAGE(PG8_SB(1, 1), b3 + hstep, voffB); PG8_STAGE(PG8_SA(1, 0), a3, voffA);
;             PG8_WAIT_V(8); PG8_WAIT_L(0); PG8_BAR; PG8_MMA(1, 0, At, B0); PG8_MMA(1, 1, At, B1); PG8_BAR; PG8_SCHED;
;         }
;         if (wr == 0) PG8_BAR;
	s_setprio 0
	s_add_i32 s29, 0, 0x18000
	v_add_u32_e32 v142, s29, v145
	s_add_i32 s30, 0, 0x1c000
	ds_read_b128 v[146:149], v142
	ds_read_b128 v[156:159], v142 offset:1024
	ds_read_b128 v[160:163], v142 offset:2048
	ds_read_b128 v[164:167], v142 offset:3072
	v_add_u32_e32 v142, s30, v145
	ds_read_b128 v[168:171], v142
	ds_read_b128 v[172:175], v142 offset:1024
	ds_read_b128 v[176:179], v142 offset:2048
	ds_read_b128 v[180:183], v142 offset:3072
	s_add_u32 s46, s56, 0x40000
	s_addc_u32 s47, s57, 0
	s_mov_b32 m0, s75
	ds_read_b128 v[184:187], v155 offset:32768
	ds_read_b128 v[188:191], v155 offset:33792
	ds_read_b128 v[192:195], v155 offset:34816
	ds_read_b128 v[204:207], v155 offset:35840
	ds_read_b128 v[208:211], v155 offset:36864
	ds_read_b128 v[212:215], v155 offset:37888
	ds_read_b128 v[216:219], v155 offset:38912
	ds_read_b128 v[220:223], v155 offset:39936
	global_load_lds_dwordx4 v134, s[46:47]
	s_mov_b32 m0, s92
	s_nop 0
	global_load_lds_dwordx4 v132, s[46:47]
	s_waitcnt vmcnt(8)
	s_waitcnt lgkmcnt(0)
	s_setprio 1
	s_barrier
	v_mfma_f32_16x16x32_bf16 v[126:129], v[146:149], v[184:187], v[126:129]
	v_mfma_f32_16x16x32_bf16 v[118:121], v[160:163], v[184:187], v[118:121]
	v_mfma_f32_16x16x32_bf16 v[110:113], v[146:149], v[192:195], v[110:113]
	v_mfma_f32_16x16x32_bf16 v[102:105], v[160:163], v[192:195], v[102:105]
	v_mfma_f32_16x16x32_bf16 v[94:97], v[146:149], v[208:211], v[94:97]
	v_mfma_f32_16x16x32_bf16 v[86:89], v[160:163], v[208:211], v[86:89]
	v_mfma_f32_16x16x32_bf16 v[78:81], v[146:149], v[216:219], v[78:81]
	v_mfma_f32_16x16x32_bf16 v[70:73], v[160:163], v[216:219], v[70:73]
	v_mfma_f32_16x16x32_bf16 v[126:129], v[156:159], v[188:191], v[126:129]
	v_mfma_f32_16x16x32_bf16 v[118:121], v[164:167], v[188:191], v[118:121]
	v_mfma_f32_16x16x32_bf16 v[110:113], v[156:159], v[204:207], v[110:113]
	v_mfma_f32_16x16x32_bf16 v[102:105], v[164:167], v[204:207], v[102:105]
	v_mfma_f32_16x16x32_bf16 v[94:97], v[156:159], v[212:215], v[94:97]
	v_mfma_f32_16x16x32_bf16 v[86:89], v[164:167], v[212:215], v[86:89]
	v_mfma_f32_16x16x32_bf16 v[78:81], v[156:159], v[220:223], v[78:81]
	v_mfma_f32_16x16x32_bf16 v[70:73], v[164:167], v[220:223], v[70:73]
	s_setprio 0
	s_setprio 1
	v_mfma_f32_16x16x32_bf16 v[122:125], v[168:171], v[184:187], v[122:125]
	v_mfma_f32_16x16x32_bf16 v[114:117], v[176:179], v[184:187], v[114:117]
	v_mfma_f32_16x16x32_bf16 v[106:109], v[168:171], v[192:195], v[106:109]
	v_mfma_f32_16x16x32_bf16 v[98:101], v[176:179], v[192:195], v[98:101]
	v_mfma_f32_16x16x32_bf16 v[90:93], v[168:171], v[208:211], v[90:93]
	v_mfma_f32_16x16x32_bf16 v[82:85], v[176:179], v[208:211], v[82:85]
	v_mfma_f32_16x16x32_bf16 v[74:77], v[168:171], v[216:219], v[74:77]
	v_mfma_f32_16x16x32_bf16 v[66:69], v[176:179], v[216:219], v[66:69]
	v_mfma_f32_16x16x32_bf16 v[122:125], v[172:175], v[188:191], v[122:125]
	v_mfma_f32_16x16x32_bf16 v[114:117], v[180:183], v[188:191], v[114:117]
	v_mfma_f32_16x16x32_bf16 v[106:109], v[172:175], v[204:207], v[106:109]
	v_mfma_f32_16x16x32_bf16 v[98:101], v[180:183], v[204:207], v[98:101]
	v_mfma_f32_16x16x32_bf16 v[90:93], v[172:175], v[212:215], v[90:93]
	v_mfma_f32_16x16x32_bf16 v[82:85], v[180:183], v[212:215], v[82:85]
	v_mfma_f32_16x16x32_bf16 v[74:77], v[172:175], v[220:223], v[74:77]
	v_mfma_f32_16x16x32_bf16 v[66:69], v[180:183], v[220:223], v[66:69]
	s_barrier
	s_setprio 0
	s_add_i32 s29, s29, s43
	s_mov_b32 m0, s29
	ds_read_b128 v[184:187], v155 offset:49152
	ds_read_b128 v[188:191], v155 offset:50176
	ds_read_b128 v[192:195], v155 offset:51200
	ds_read_b128 v[204:207], v155 offset:52224
	ds_read_b128 v[208:211], v155 offset:53248
	ds_read_b128 v[212:215], v155 offset:54272
	ds_read_b128 v[216:219], v155 offset:55296
	ds_read_b128 v[220:223], v155 offset:56320
	global_load_lds_dwordx4 v141, s[20:21]
	s_add_i32 m0, s29, 0x2000
	s_add_i32 s29, s30, s43
	global_load_lds_dwordx4 v153, s[20:21]
	s_add_u32 s20, s20, 0x40080
	s_addc_u32 s21, s21, 0
	s_mov_b32 m0, s29
	s_nop 0
	global_load_lds_dwordx4 v0, s[20:21]
	s_add_i32 m0, s29, 0x2000
	s_nop 0
	global_load_lds_dwordx4 v130, s[20:21]
	s_mov_b32 m0, s93
	s_nop 0
	global_load_lds_dwordx4 v201, s[56:57]
	s_mov_b32 m0, s44
	s_nop 0
	global_load_lds_dwordx4 v225, s[56:57]
	s_waitcnt vmcnt(8)
	s_waitcnt lgkmcnt(0)
	s_setprio 1
	s_barrier
	v_mfma_f32_16x16x32_bf16 v[62:65], v[146:149], v[184:187], v[62:65]
	v_mfma_f32_16x16x32_bf16 v[54:57], v[160:163], v[184:187], v[54:57]
	v_mfma_f32_16x16x32_bf16 v[46:49], v[146:149], v[192:195], v[46:49]
	v_mfma_f32_16x16x32_bf16 v[38:41], v[160:163], v[192:195], v[38:41]
	v_mfma_f32_16x16x32_bf16 v[30:33], v[146:149], v[208:211], v[30:33]
	v_mfma_f32_16x16x32_bf16 v[22:25], v[160:163], v[208:211], v[22:25]
	v_mfma_f32_16x16x32_bf16 v[14:17], v[146:149], v[216:219], v[14:17]
	v_mfma_f32_16x16x32_bf16 v[6:9], v[160:163], v[216:219], v[6:9]
	v_mfma_f32_16x16x32_bf16 v[62:65], v[156:159], v[188:191], v[62:65]
	v_mfma_f32_16x16x32_bf16 v[54:57], v[164:167], v[188:191], v[54:57]
	v_mfma_f32_16x16x32_bf16 v[46:49], v[156:159], v[204:207], v[46:49]
	v_mfma_f32_16x16x32_bf16 v[38:41], v[164:167], v[204:207], v[38:41]
	v_mfma_f32_16x16x32_bf16 v[30:33], v[156:159], v[212:215], v[30:33]
	v_mfma_f32_16x16x32_bf16 v[22:25], v[164:167], v[212:215], v[22:25]
	v_mfma_f32_16x16x32_bf16 v[14:17], v[156:159], v[220:223], v[14:17]
	v_mfma_f32_16x16x32_bf16 v[6:9], v[164:167], v[220:223], v[6:9]
	s_setprio 0
	s_setprio 1
	v_mfma_f32_16x16x32_bf16 v[58:61], v[168:171], v[184:187], v[58:61]
	v_mfma_f32_16x16x32_bf16 v[50:53], v[176:179], v[184:187], v[50:53]
	v_mfma_f32_16x16x32_bf16 v[42:45], v[168:171], v[192:195], v[42:45]
	v_mfma_f32_16x16x32_bf16 v[34:37], v[176:179], v[192:195], v[34:37]
	v_mfma_f32_16x16x32_bf16 v[26:29], v[168:171], v[208:211], v[26:29]
	v_mfma_f32_16x16x32_bf16 v[18:21], v[176:179], v[208:211], v[18:21]
	v_mfma_f32_16x16x32_bf16 v[10:13], v[168:171], v[216:219], v[10:13]
	v_mfma_f32_16x16x32_bf16 v[2:5], v[176:179], v[216:219], v[2:5]
	v_mfma_f32_16x16x32_bf16 v[58:61], v[172:175], v[188:191], v[58:61]
	v_mfma_f32_16x16x32_bf16 v[50:53], v[180:183], v[188:191], v[50:53]
	v_mfma_f32_16x16x32_bf16 v[42:45], v[172:175], v[204:207], v[42:45]
	v_mfma_f32_16x16x32_bf16 v[34:37], v[180:183], v[204:207], v[34:37]
	v_mfma_f32_16x16x32_bf16 v[26:29], v[172:175], v[212:215], v[26:29]
	v_mfma_f32_16x16x32_bf16 v[18:21], v[180:183], v[212:215], v[18:21]
	v_mfma_f32_16x16x32_bf16 v[10:13], v[172:175], v[220:223], v[10:13]
	v_mfma_f32_16x16x32_bf16 v[2:5], v[180:183], v[220:223], v[2:5]
	s_barrier
	s_setprio 0
	s_add_i32 s31, s31, 2
	s_add_u32 s23, s23, 0x100
	s_addc_u32 s24, s24, 0
	s_add_u32 s16, s16, 0x100
	s_addc_u32 s17, s17, 0
	s_cmp_gt_u32 s31, 13
	s_cbranch_scc0 .LBB0_369
	s_and_b64 vcc, exec, s[6:7]
	s_cbranch_vccz .LBB0_372
	s_and_b64 vcc, exec, s[2:3]
	s_cbranch_vccnz .LBB0_372
	s_barrier

; __device__ __forceinline__ unsigned pk2(float lo, float hi) { f32x2 v = {lo, hi}; bf16x2_t b = __builtin_convertvector(v, bf16x2_t); return __builtin_bit_cast(unsigned, b); }
; __device__ __forceinline__ float sigmoidf_(float x) { return __builtin_amdgcn_rcpf(1.0f + __builtin_amdgcn_exp2f(-x * LOG2E)); }
;     __device__ __forceinline__ void operator()(const f32x4 (&acc)[2][2][4][2], const Unit& u, int wr, int wc, int fr, int fq, LAS unsigned char* lds, int tid) const {
;     ...
;         for (int ai = 0; ai < 2; ++ai)
; #pragma unroll
;             for (int m = 0; m < 4; ++m) { const size_t row = (size_t)(row0 + ai * HALF + m * 16); const float rs = rsv[ai][m]; gbf16* rowp = O + row * FF + col0;
;                 float h[8];
; #pragma unroll
;                 for (int n = 0; n < 2; ++n)
; #pragma unroll
;                     for (int e = 0; e < 4; ++e) { const float g = acc[ai][0][m][n][e] * rs, uu = acc[ai][1][m][n][e] * rs; h[n * 4 + e] = g * sigmoidf_(g) * uu; }
;                 u32x4 w; w.x = pk2(h[0], h[1]); w.y = pk2(h[2], h[3]); w.z = pk2(h[4], h[5]); w.w = pk2(h[6], h[7]);
;                 *(gu32x4*)rowp = w; }
.Lk8_rs_hit:
	s_andn2_b64 vcc, exec, s[2:3]
	v_lshl_or_b32 v174, s1, 7, v151
	v_mov_b32_e32 v170, v226
	v_mov_b32_e32 v166, v236
	v_mov_b32_e32 v162, v237
	v_mov_b32_e32 v158, v244
	v_mov_b32_e32 v154, v245
	v_mov_b32_e32 v150, v246
	v_mov_b32_e32 v144, v247
	v_mov_b32_e32 v142, v248
	v_pk_mul_f32 v[126:127], v[126:127], v[170:171] op_sel_hi:[1,0]
	v_mul_f32_e32 v141, 0xbfb8aa3b, v126
	v_exp_f32_e32 v141, v141
	v_pk_mul_f32 v[122:123], v[122:123], v[170:171] op_sel_hi:[1,0]
	v_pk_mul_f32 v[124:125], v[124:125], v[170:171] op_sel_hi:[1,0]
	v_pk_mul_f32 v[118:119], v[118:119], v[170:171] op_sel_hi:[1,0]
	v_add_f32_e32 v141, 1.0, v141
	v_rcp_f32_e32 v176, v141
	v_mul_f32_e32 v141, 0xbfb8aa3b, v127
	v_exp_f32_e32 v141, v141
	v_pk_mul_f32 v[114:115], v[114:115], v[170:171] op_sel_hi:[1,0]
	v_ashrrev_i32_e32 v175, 31, v174
	v_mov_b64_e32 v[148:149], s[88:89]
	v_add_f32_e32 v141, 1.0, v141
	v_rcp_f32_e32 v177, v141
	v_pk_mul_f32 v[116:117], v[116:117], v[170:171] op_sel_hi:[1,0]
	v_mad_i64_i32 v[172:173], s[0:1], v172, s79, v[148:149]
	v_pk_mul_f32 v[126:127], v[126:127], v[176:177]
	v_pk_mul_f32 v[110:111], v[110:111], v[166:167] op_sel_hi:[1,0]
	v_pk_mul_f32 v[122:123], v[122:123], v[126:127]
	v_pk_mul_f32 v[126:127], v[128:129], v[170:171] op_sel_hi:[1,0]
	v_pk_mul_f32 v[106:107], v[106:107], v[166:167] op_sel_hi:[1,0]
	v_mul_f32_e32 v128, 0xbfb8aa3b, v126
	v_mul_f32_e32 v129, 0xbfb8aa3b, v127
	v_exp_f32_e32 v128, v128
	v_exp_f32_e32 v129, v129
	v_pk_mul_f32 v[108:109], v[108:109], v[166:167] op_sel_hi:[1,0]
	v_pk_mul_f32 v[102:103], v[102:103], v[166:167] op_sel_hi:[1,0]
	v_add_f32_e32 v128, 1.0, v128
	v_add_f32_e32 v129, 1.0, v129
	v_rcp_f32_e32 v128, v128
	v_rcp_f32_e32 v129, v129
	v_pk_mul_f32 v[98:99], v[98:99], v[166:167] op_sel_hi:[1,0]
	v_pk_mul_f32 v[100:101], v[100:101], v[166:167] op_sel_hi:[1,0]
	v_pk_mul_f32 v[94:95], v[94:95], v[162:163] op_sel_hi:[1,0]
	v_pk_mul_f32 v[126:127], v[126:127], v[128:129]
	v_pk_mul_f32 v[90:91], v[90:91], v[162:163] op_sel_hi:[1,0]
	v_pk_mul_f32 v[124:125], v[124:125], v[126:127]
	v_mul_f32_e32 v126, 0xbfb8aa3b, v118
	v_mul_f32_e32 v127, 0xbfb8aa3b, v119
	v_exp_f32_e32 v126, v126
	v_exp_f32_e32 v127, v127
	v_pk_mul_f32 v[92:93], v[92:93], v[162:163] op_sel_hi:[1,0]
	v_pk_mul_f32 v[86:87], v[86:87], v[162:163] op_sel_hi:[1,0]
	v_add_f32_e32 v126, 1.0, v126
	v_add_f32_e32 v127, 1.0, v127
	v_rcp_f32_e32 v126, v126
	v_rcp_f32_e32 v127, v127
	v_pk_mul_f32 v[82:83], v[82:83], v[162:163] op_sel_hi:[1,0]
	v_pk_mul_f32 v[84:85], v[84:85], v[162:163] op_sel_hi:[1,0]
	v_pk_mul_f32 v[78:79], v[78:79], v[158:159] op_sel_hi:[1,0]
	v_pk_mul_f32 v[118:119], v[118:119], v[126:127]
	v_pk_mul_f32 v[74:75], v[74:75], v[158:159] op_sel_hi:[1,0]
	v_pk_mul_f32 v[118:119], v[114:115], v[118:119]
	v_pk_mul_f32 v[114:115], v[120:121], v[170:171] op_sel_hi:[1,0]
	v_cvt_pk_bf16_f32 v118, v118, v119
	v_mul_f32_e32 v120, 0xbfb8aa3b, v114
	v_mul_f32_e32 v121, 0xbfb8aa3b, v115
	v_exp_f32_e32 v120, v120
	v_exp_f32_e32 v121, v121
	v_pk_mul_f32 v[76:77], v[76:77], v[158:159] op_sel_hi:[1,0]
	v_pk_mul_f32 v[70:71], v[70:71], v[158:159] op_sel_hi:[1,0]
	v_add_f32_e32 v120, 1.0, v120
	v_add_f32_e32 v121, 1.0, v121
	v_rcp_f32_e32 v120, v120
	v_rcp_f32_e32 v121, v121
	v_pk_mul_f32 v[66:67], v[66:67], v[158:159] op_sel_hi:[1,0]
	v_pk_mul_f32 v[68:69], v[68:69], v[158:159] op_sel_hi:[1,0]
	v_pk_mul_f32 v[62:63], v[62:63], v[154:155] op_sel_hi:[1,0]
	v_pk_mul_f32 v[114:115], v[114:115], v[120:121]
	v_pk_mul_f32 v[58:59], v[58:59], v[154:155] op_sel_hi:[1,0]
	v_pk_mul_f32 v[120:121], v[116:117], v[114:115]
	v_lshlrev_b64 v[114:115], 1, v[174:175]
	v_lshl_add_u64 v[126:127], v[172:173], 0, v[114:115]
	v_cvt_pk_bf16_f32 v116, v122, v123
	v_cvt_pk_bf16_f32 v117, v124, v125
	v_cvt_pk_bf16_f32 v119, v120, v121
	global_store_dwordx4 v[126:127], v[116:119], off
	v_pk_mul_f32 v[60:61], v[60:61], v[154:155] op_sel_hi:[1,0]
	v_pk_mul_f32 v[54:55], v[54:55], v[154:155] op_sel_hi:[1,0]
	v_mul_f32_e32 v118, 0xbfb8aa3b, v110
	v_mul_f32_e32 v119, 0xbfb8aa3b, v111
	v_exp_f32_e32 v118, v118
	v_exp_f32_e32 v119, v119
	v_mad_i64_i32 v[116:117], s[0:1], v168, s79, v[148:149]
	v_add_f32_e32 v118, 1.0, v118
	v_add_f32_e32 v119, 1.0, v119
	v_rcp_f32_e32 v118, v118
	v_rcp_f32_e32 v119, v119
	v_pk_mul_f32 v[50:51], v[50:51], v[154:155] op_sel_hi:[1,0]
	v_pk_mul_f32 v[52:53], v[52:53], v[154:155] op_sel_hi:[1,0]
	v_pk_mul_f32 v[46:47], v[46:47], v[150:151] op_sel_hi:[1,0]
	v_pk_mul_f32 v[110:111], v[110:111], v[118:119]
	v_pk_mul_f32 v[42:43], v[42:43], v[150:151] op_sel_hi:[1,0]
	v_pk_mul_f32 v[106:107], v[106:107], v[110:111]
	v_pk_mul_f32 v[110:111], v[112:113], v[166:167] op_sel_hi:[1,0]
	v_pk_mul_f32 v[44:45], v[44:45], v[150:151] op_sel_hi:[1,0]
	v_mul_f32_e32 v112, 0xbfb8aa3b, v110
	v_mul_f32_e32 v113, 0xbfb8aa3b, v111
	v_exp_f32_e32 v112, v112
	v_exp_f32_e32 v113, v113
	v_pk_mul_f32 v[38:39], v[38:39], v[150:151] op_sel_hi:[1,0]
	v_pk_mul_f32 v[34:35], v[34:35], v[150:151] op_sel_hi:[1,0]
	v_add_f32_e32 v112, 1.0, v112
	v_add_f32_e32 v113, 1.0, v113
	v_rcp_f32_e32 v112, v112
	v_rcp_f32_e32 v113, v113
	v_pk_mul_f32 v[36:37], v[36:37], v[150:151] op_sel_hi:[1,0]
	v_pk_mul_f32 v[30:31], v[30:31], v[144:145] op_sel_hi:[1,0]
	v_pk_mul_f32 v[26:27], v[26:27], v[144:145] op_sel_hi:[1,0]
	v_pk_mul_f32 v[110:111], v[110:111], v[112:113]
	v_pk_mul_f32 v[28:29], v[28:29], v[144:145] op_sel_hi:[1,0]
	v_pk_mul_f32 v[108:109], v[108:109], v[110:111]
	v_mul_f32_e32 v110, 0xbfb8aa3b, v102
	v_mul_f32_e32 v111, 0xbfb8aa3b, v103
	v_exp_f32_e32 v110, v110
	v_exp_f32_e32 v111, v111
	v_pk_mul_f32 v[22:23], v[22:23], v[144:145] op_sel_hi:[1,0]
	v_pk_mul_f32 v[18:19], v[18:19], v[144:145] op_sel_hi:[1,0]
; __device__ __forceinline__ unsigned pk2(float lo, float hi) { f32x2 v = {lo, hi}; bf16x2_t b = __builtin_convertvector(v, bf16x2_t); return __builtin_bit_cast(unsigned, b); }
; __device__ __forceinline__ float sigmoidf_(float x) { return __builtin_amdgcn_rcpf(1.0f + __builtin_amdgcn_exp2f(-x * LOG2E)); }
;     __device__ __forceinline__ void operator()(const f32x4 (&acc)[2][2][4][2], const Unit& u, int wr, int wc, int fr, int fq, LAS unsigned char* lds, int tid) const {
;     ...
;         for (int ai = 0; ai < 2; ++ai)
; #pragma unroll
;             for (int m = 0; m < 4; ++m) { const size_t row = (size_t)(row0 + ai * HALF + m * 16); const float rs = rsv[ai][m]; gbf16* rowp = O + row * FF + col0;
;                 float h[8];
; #pragma unroll
;                 for (int n = 0; n < 2; ++n)
; #pragma unroll
;                     for (int e = 0; e < 4; ++e) { const float g = acc[ai][0][m][n][e] * rs, uu = acc[ai][1][m][n][e] * rs; h[n * 4 + e] = g * sigmoidf_(g) * uu; }
;                 u32x4 w; w.x = pk2(h[0], h[1]); w.y = pk2(h[2], h[3]); w.z = pk2(h[4], h[5]); w.w = pk2(h[6], h[7]);
;                 *(gu32x4*)rowp = w; }
	v_add_f32_e32 v110, 1.0, v110
	v_add_f32_e32 v111, 1.0, v111
	v_rcp_f32_e32 v110, v110
	v_rcp_f32_e32 v111, v111
	v_pk_mul_f32 v[20:21], v[20:21], v[144:145] op_sel_hi:[1,0]
	v_pk_mul_f32 v[14:15], v[14:15], v[142:143] op_sel_hi:[1,0]
	v_pk_mul_f32 v[10:11], v[10:11], v[142:143] op_sel_hi:[1,0]
	v_pk_mul_f32 v[102:103], v[102:103], v[110:111]
	v_lshl_add_u64 v[110:111], v[116:117], 0, v[114:115]
	v_pk_mul_f32 v[102:103], v[98:99], v[102:103]
	v_pk_mul_f32 v[98:99], v[104:105], v[166:167] op_sel_hi:[1,0]
	v_pk_mul_f32 v[12:13], v[12:13], v[142:143] op_sel_hi:[1,0]
	v_mul_f32_e32 v104, 0xbfb8aa3b, v98
	v_mul_f32_e32 v105, 0xbfb8aa3b, v99
	v_exp_f32_e32 v104, v104
	v_exp_f32_e32 v105, v105
	v_pk_mul_f32 v[6:7], v[6:7], v[142:143] op_sel_hi:[1,0]
	v_pk_mul_f32 v[2:3], v[2:3], v[142:143] op_sel_hi:[1,0]
	v_add_f32_e32 v104, 1.0, v104
	v_add_f32_e32 v105, 1.0, v105
	v_rcp_f32_e32 v104, v104
	v_rcp_f32_e32 v105, v105
	v_pk_mul_f32 v[4:5], v[4:5], v[142:143] op_sel_hi:[1,0]
	v_pk_mul_f32 v[98:99], v[98:99], v[104:105]
	s_nop 0
	v_pk_mul_f32 v[104:105], v[100:101], v[98:99]
	v_cvt_pk_bf16_f32 v98, v106, v107
	v_cvt_pk_bf16_f32 v99, v108, v109
	v_cvt_pk_bf16_f32 v100, v102, v103
	v_cvt_pk_bf16_f32 v101, v104, v105
	global_store_dwordx4 v[110:111], v[98:101], off
	s_nop 1
	v_mul_f32_e32 v100, 0xbfb8aa3b, v94
	v_mul_f32_e32 v101, 0xbfb8aa3b, v95
	v_exp_f32_e32 v100, v100
	v_exp_f32_e32 v101, v101
	v_mad_i64_i32 v[98:99], s[0:1], v164, s79, v[148:149]
	v_add_f32_e32 v100, 1.0, v100
	v_add_f32_e32 v101, 1.0, v101
	v_rcp_f32_e32 v100, v100
	v_rcp_f32_e32 v101, v101
	s_nop 0
	v_pk_mul_f32 v[94:95], v[94:95], v[100:101]
	s_nop 0
	v_pk_mul_f32 v[90:91], v[90:91], v[94:95]
	v_pk_mul_f32 v[94:95], v[96:97], v[162:163] op_sel_hi:[1,0]
	s_nop 0
	v_mul_f32_e32 v96, 0xbfb8aa3b, v94
	v_mul_f32_e32 v97, 0xbfb8aa3b, v95
	v_exp_f32_e32 v96, v96
	v_exp_f32_e32 v97, v97
	v_add_f32_e32 v96, 1.0, v96
	v_add_f32_e32 v97, 1.0, v97
	v_rcp_f32_e32 v96, v96
	v_rcp_f32_e32 v97, v97
	s_nop 0
	v_pk_mul_f32 v[94:95], v[94:95], v[96:97]
	s_nop 0
	v_pk_mul_f32 v[92:93], v[92:93], v[94:95]
	v_mul_f32_e32 v94, 0xbfb8aa3b, v86
	v_mul_f32_e32 v95, 0xbfb8aa3b, v87
	v_exp_f32_e32 v94, v94
	v_exp_f32_e32 v95, v95
	v_add_f32_e32 v94, 1.0, v94
	v_add_f32_e32 v95, 1.0, v95
	v_rcp_f32_e32 v94, v94
	v_rcp_f32_e32 v95, v95
	s_nop 0
	v_pk_mul_f32 v[86:87], v[86:87], v[94:95]
	s_nop 0
	v_pk_mul_f32 v[86:87], v[82:83], v[86:87]
	v_pk_mul_f32 v[82:83], v[88:89], v[162:163] op_sel_hi:[1,0]
	v_lshl_add_u64 v[94:95], v[98:99], 0, v[114:115]
	v_mul_f32_e32 v88, 0xbfb8aa3b, v82
	v_mul_f32_e32 v89, 0xbfb8aa3b, v83
	v_exp_f32_e32 v88, v88
	v_exp_f32_e32 v89, v89
	v_add_f32_e32 v88, 1.0, v88
	v_add_f32_e32 v89, 1.0, v89
	v_rcp_f32_e32 v88, v88
	v_rcp_f32_e32 v89, v89
	s_nop 0
	v_pk_mul_f32 v[82:83], v[82:83], v[88:89]
	s_nop 0
	v_pk_mul_f32 v[88:89], v[84:85], v[82:83]
	v_cvt_pk_bf16_f32 v82, v90, v91
	v_cvt_pk_bf16_f32 v83, v92, v93
	v_cvt_pk_bf16_f32 v84, v86, v87
	v_cvt_pk_bf16_f32 v85, v88, v89
	global_store_dwordx4 v[94:95], v[82:85], off
	s_nop 1
	v_mul_f32_e32 v84, 0xbfb8aa3b, v78
	v_mul_f32_e32 v85, 0xbfb8aa3b, v79
	v_exp_f32_e32 v84, v84
	v_exp_f32_e32 v85, v85
	v_mad_i64_i32 v[82:83], s[0:1], v160, s79, v[148:149]
	v_add_f32_e32 v84, 1.0, v84
	v_add_f32_e32 v85, 1.0, v85
	v_rcp_f32_e32 v84, v84
	v_rcp_f32_e32 v85, v85
	s_nop 0
	v_pk_mul_f32 v[78:79], v[78:79], v[84:85]
	s_nop 0
	v_pk_mul_f32 v[74:75], v[74:75], v[78:79]
	v_pk_mul_f32 v[78:79], v[80:81], v[158:159] op_sel_hi:[1,0]
	s_nop 0
	v_mul_f32_e32 v80, 0xbfb8aa3b, v78
	v_mul_f32_e32 v81, 0xbfb8aa3b, v79
	v_exp_f32_e32 v80, v80
	v_exp_f32_e32 v81, v81
	v_add_f32_e32 v80, 1.0, v80
	v_add_f32_e32 v81, 1.0, v81
	v_rcp_f32_e32 v80, v80
	v_rcp_f32_e32 v81, v81
	s_nop 0
	v_pk_mul_f32 v[78:79], v[78:79], v[80:81]
	s_nop 0
	v_pk_mul_f32 v[76:77], v[76:77], v[78:79]
	v_mul_f32_e32 v78, 0xbfb8aa3b, v70
	v_mul_f32_e32 v79, 0xbfb8aa3b, v71
	v_exp_f32_e32 v78, v78
	v_exp_f32_e32 v79, v79
	v_add_f32_e32 v78, 1.0, v78
	v_add_f32_e32 v79, 1.0, v79
	v_rcp_f32_e32 v78, v78
	v_rcp_f32_e32 v79, v79
	s_nop 0
	v_pk_mul_f32 v[70:71], v[70:71], v[78:79]
	s_nop 0
	v_pk_mul_f32 v[70:71], v[66:67], v[70:71]
	v_pk_mul_f32 v[66:67], v[72:73], v[158:159] op_sel_hi:[1,0]
	v_lshl_add_u64 v[78:79], v[82:83], 0, v[114:115]
	v_mul_f32_e32 v72, 0xbfb8aa3b, v66
	v_mul_f32_e32 v73, 0xbfb8aa3b, v67
	v_exp_f32_e32 v72, v72
	v_exp_f32_e32 v73, v73
	v_add_f32_e32 v72, 1.0, v72
	v_add_f32_e32 v73, 1.0, v73
	v_rcp_f32_e32 v72, v72
	v_rcp_f32_e32 v73, v73
	s_nop 0
	v_pk_mul_f32 v[66:67], v[66:67], v[72:73]
	s_nop 0
	v_pk_mul_f32 v[72:73], v[68:69], v[66:67]
	v_cvt_pk_bf16_f32 v66, v74, v75
	v_cvt_pk_bf16_f32 v67, v76, v77
	v_cvt_pk_bf16_f32 v68, v70, v71
	v_cvt_pk_bf16_f32 v69, v72, v73
	global_store_dwordx4 v[78:79], v[66:69], off
	s_nop 1
	v_mul_f32_e32 v68, 0xbfb8aa3b, v62
	v_mul_f32_e32 v69, 0xbfb8aa3b, v63
	v_exp_f32_e32 v68, v68
	v_exp_f32_e32 v69, v69
	v_mad_i64_i32 v[66:67], s[0:1], v156, s79, v[148:149]
	v_add_f32_e32 v68, 1.0, v68
	v_add_f32_e32 v69, 1.0, v69
	v_rcp_f32_e32 v68, v68
	v_rcp_f32_e32 v69, v69
	s_nop 0
	v_pk_mul_f32 v[62:63], v[62:63], v[68:69]
	s_nop 0
	v_pk_mul_f32 v[58:59], v[58:59], v[62:63]
	v_pk_mul_f32 v[62:63], v[64:65], v[154:155] op_sel_hi:[1,0]
	s_nop 0
	v_mul_f32_e32 v64, 0xbfb8aa3b, v62
	v_mul_f32_e32 v65, 0xbfb8aa3b, v63
	v_exp_f32_e32 v64, v64
	v_exp_f32_e32 v65, v65
	v_add_f32_e32 v64, 1.0, v64
	v_add_f32_e32 v65, 1.0, v65
	v_rcp_f32_e32 v64, v64
	v_rcp_f32_e32 v65, v65
	s_nop 0
	v_pk_mul_f32 v[62:63], v[62:63], v[64:65]
	s_nop 0
	v_pk_mul_f32 v[60:61], v[60:61], v[62:63]
	v_mul_f32_e32 v62, 0xbfb8aa3b, v54
	v_mul_f32_e32 v63, 0xbfb8aa3b, v55
; __device__ __forceinline__ unsigned pk2(float lo, float hi) { f32x2 v = {lo, hi}; bf16x2_t b = __builtin_convertvector(v, bf16x2_t); return __builtin_bit_cast(unsigned, b); }
; __device__ __forceinline__ float sigmoidf_(float x) { return __builtin_amdgcn_rcpf(1.0f + __builtin_amdgcn_exp2f(-x * LOG2E)); }
; #define PG8_BAR __builtin_amdgcn_s_barrier()
;     __device__ __forceinline__ void operator()(const f32x4 (&acc)[2][2][4][2], const Unit& u, int wr, int wc, int fr, int fq, LAS unsigned char* lds, int tid) const {
;     ...
;         for (int ai = 0; ai < 2; ++ai)
; #pragma unroll
;             for (int m = 0; m < 4; ++m) { const size_t row = (size_t)(row0 + ai * HALF + m * 16); const float rs = rsv[ai][m]; gbf16* rowp = O + row * FF + col0;
;                 float h[8];
; #pragma unroll
;                 for (int n = 0; n < 2; ++n)
; #pragma unroll
;                     for (int e = 0; e < 4; ++e) { const float g = acc[ai][0][m][n][e] * rs, uu = acc[ai][1][m][n][e] * rs; h[n * 4 + e] = g * sigmoidf_(g) * uu; }
;                 u32x4 w; w.x = pk2(h[0], h[1]); w.y = pk2(h[2], h[3]); w.z = pk2(h[4], h[5]); w.w = pk2(h[6], h[7]);
;                 *(gu32x4*)rowp = w; }
; template <class Epi, class Sched>
; __device__ __forceinline__ void gemm_phase(LAS unsigned char* lds, const int tid, const Gemm g, const Sched& S, const Epi& E) {
;     ...
;         if (!has_next) break;
; #pragma unroll
;         for (int a = 0; a < 2; ++a)
; #pragma unroll
;             for (int b = 0; b < 2; ++b)
; #pragma unroll
;                 for (int m = 0; m < 4; ++m)
; #pragma unroll
;                     for (int n = 0; n < 2; ++n) acc[a][b][m][n] = (f32x4){0.f, 0.f, 0.f, 0.f};
;         cur = nxt; cA = nA; cB = nB; ++ui;
;         if (wr == 1) PG8_BAR;
	v_exp_f32_e32 v62, v62
	v_exp_f32_e32 v63, v63
	v_add_f32_e32 v62, 1.0, v62
	v_add_f32_e32 v63, 1.0, v63
	v_rcp_f32_e32 v62, v62
	v_rcp_f32_e32 v63, v63
	s_nop 0
	v_pk_mul_f32 v[54:55], v[54:55], v[62:63]
	s_nop 0
	v_pk_mul_f32 v[54:55], v[50:51], v[54:55]
	v_pk_mul_f32 v[50:51], v[56:57], v[154:155] op_sel_hi:[1,0]
	v_lshl_add_u64 v[62:63], v[66:67], 0, v[114:115]
	v_mul_f32_e32 v56, 0xbfb8aa3b, v50
	v_mul_f32_e32 v57, 0xbfb8aa3b, v51
	v_exp_f32_e32 v56, v56
	v_exp_f32_e32 v57, v57
	v_add_f32_e32 v56, 1.0, v56
	v_add_f32_e32 v57, 1.0, v57
	v_rcp_f32_e32 v56, v56
	v_rcp_f32_e32 v57, v57
	s_nop 0
	v_pk_mul_f32 v[50:51], v[50:51], v[56:57]
	s_nop 0
	v_pk_mul_f32 v[56:57], v[52:53], v[50:51]
	v_cvt_pk_bf16_f32 v50, v58, v59
	v_cvt_pk_bf16_f32 v51, v60, v61
	v_cvt_pk_bf16_f32 v52, v54, v55
	v_cvt_pk_bf16_f32 v53, v56, v57
	global_store_dwordx4 v[62:63], v[50:53], off
	s_nop 1
	v_mul_f32_e32 v52, 0xbfb8aa3b, v46
	v_mul_f32_e32 v53, 0xbfb8aa3b, v47
	v_exp_f32_e32 v52, v52
	v_exp_f32_e32 v53, v53
	v_mad_i64_i32 v[50:51], s[0:1], v152, s79, v[148:149]
	v_add_f32_e32 v52, 1.0, v52
	v_add_f32_e32 v53, 1.0, v53
	v_rcp_f32_e32 v52, v52
	v_rcp_f32_e32 v53, v53
	s_nop 0
	v_pk_mul_f32 v[46:47], v[46:47], v[52:53]
	s_nop 0
	v_pk_mul_f32 v[42:43], v[42:43], v[46:47]
	v_pk_mul_f32 v[46:47], v[48:49], v[150:151] op_sel_hi:[1,0]
	s_nop 0
	v_mul_f32_e32 v48, 0xbfb8aa3b, v46
	v_mul_f32_e32 v49, 0xbfb8aa3b, v47
	v_exp_f32_e32 v48, v48
	v_exp_f32_e32 v49, v49
	v_add_f32_e32 v48, 1.0, v48
	v_add_f32_e32 v49, 1.0, v49
	v_rcp_f32_e32 v48, v48
	v_rcp_f32_e32 v49, v49
	s_nop 0
	v_pk_mul_f32 v[46:47], v[46:47], v[48:49]
	s_nop 0
	v_pk_mul_f32 v[44:45], v[44:45], v[46:47]
	v_mul_f32_e32 v46, 0xbfb8aa3b, v38
	v_mul_f32_e32 v47, 0xbfb8aa3b, v39
	v_exp_f32_e32 v46, v46
	v_exp_f32_e32 v47, v47
	v_add_f32_e32 v46, 1.0, v46
	v_add_f32_e32 v47, 1.0, v47
	v_rcp_f32_e32 v46, v46
	v_rcp_f32_e32 v47, v47
	s_nop 0
	v_pk_mul_f32 v[38:39], v[38:39], v[46:47]
	s_nop 0
	v_pk_mul_f32 v[38:39], v[34:35], v[38:39]
	v_pk_mul_f32 v[34:35], v[40:41], v[150:151] op_sel_hi:[1,0]
	v_lshl_add_u64 v[46:47], v[50:51], 0, v[114:115]
	v_mul_f32_e32 v40, 0xbfb8aa3b, v34
	v_mul_f32_e32 v41, 0xbfb8aa3b, v35
	v_exp_f32_e32 v40, v40
	v_exp_f32_e32 v41, v41
	v_add_f32_e32 v40, 1.0, v40
	v_add_f32_e32 v41, 1.0, v41
	v_rcp_f32_e32 v40, v40
	v_rcp_f32_e32 v41, v41
	s_nop 0
	v_pk_mul_f32 v[34:35], v[34:35], v[40:41]
	s_nop 0
	v_pk_mul_f32 v[40:41], v[36:37], v[34:35]
	v_cvt_pk_bf16_f32 v34, v42, v43
	v_cvt_pk_bf16_f32 v35, v44, v45
	v_cvt_pk_bf16_f32 v36, v38, v39
	v_cvt_pk_bf16_f32 v37, v40, v41
	global_store_dwordx4 v[46:47], v[34:37], off
	s_nop 1
	v_mul_f32_e32 v36, 0xbfb8aa3b, v30
	v_mul_f32_e32 v37, 0xbfb8aa3b, v31
	v_exp_f32_e32 v36, v36
	v_exp_f32_e32 v37, v37
	v_mad_i64_i32 v[34:35], s[0:1], v146, s79, v[148:149]
	v_add_f32_e32 v36, 1.0, v36
	v_add_f32_e32 v37, 1.0, v37
	v_rcp_f32_e32 v36, v36
	v_rcp_f32_e32 v37, v37
	s_nop 0
	v_pk_mul_f32 v[30:31], v[30:31], v[36:37]
	s_nop 0
	v_pk_mul_f32 v[26:27], v[26:27], v[30:31]
	v_pk_mul_f32 v[30:31], v[32:33], v[144:145] op_sel_hi:[1,0]
	s_nop 0
	v_mul_f32_e32 v32, 0xbfb8aa3b, v30
	v_mul_f32_e32 v33, 0xbfb8aa3b, v31
	v_exp_f32_e32 v32, v32
	v_exp_f32_e32 v33, v33
	v_add_f32_e32 v32, 1.0, v32
	v_add_f32_e32 v33, 1.0, v33
	v_rcp_f32_e32 v32, v32
	v_rcp_f32_e32 v33, v33
	s_nop 0
	v_pk_mul_f32 v[30:31], v[30:31], v[32:33]
	s_nop 0
	v_pk_mul_f32 v[28:29], v[28:29], v[30:31]
	v_mul_f32_e32 v30, 0xbfb8aa3b, v22
	v_mul_f32_e32 v31, 0xbfb8aa3b, v23
	v_exp_f32_e32 v30, v30
	v_exp_f32_e32 v31, v31
	v_add_f32_e32 v30, 1.0, v30
	v_add_f32_e32 v31, 1.0, v31
	v_rcp_f32_e32 v30, v30
	v_rcp_f32_e32 v31, v31
	s_nop 0
	v_pk_mul_f32 v[22:23], v[22:23], v[30:31]
	s_nop 0
	v_pk_mul_f32 v[22:23], v[18:19], v[22:23]
	v_pk_mul_f32 v[18:19], v[24:25], v[144:145] op_sel_hi:[1,0]
	v_lshl_add_u64 v[30:31], v[34:35], 0, v[114:115]
	v_mul_f32_e32 v24, 0xbfb8aa3b, v18
	v_mul_f32_e32 v25, 0xbfb8aa3b, v19
	v_exp_f32_e32 v24, v24
	v_exp_f32_e32 v25, v25
	v_add_f32_e32 v24, 1.0, v24
	v_add_f32_e32 v25, 1.0, v25
	v_rcp_f32_e32 v24, v24
	v_rcp_f32_e32 v25, v25
	s_nop 0
	v_pk_mul_f32 v[18:19], v[18:19], v[24:25]
	s_nop 0
	v_pk_mul_f32 v[24:25], v[20:21], v[18:19]
	v_cvt_pk_bf16_f32 v18, v26, v27
	v_cvt_pk_bf16_f32 v19, v28, v29
	v_cvt_pk_bf16_f32 v20, v22, v23
	v_cvt_pk_bf16_f32 v21, v24, v25
	global_store_dwordx4 v[30:31], v[18:21], off
	s_nop 1
	v_mul_f32_e32 v20, 0xbfb8aa3b, v14
	v_mul_f32_e32 v21, 0xbfb8aa3b, v15
	v_exp_f32_e32 v20, v20
	v_exp_f32_e32 v21, v21
	v_mad_i64_i32 v[18:19], s[0:1], v140, s79, v[148:149]
	v_add_f32_e32 v20, 1.0, v20
	v_add_f32_e32 v21, 1.0, v21
	v_rcp_f32_e32 v20, v20
	v_rcp_f32_e32 v21, v21
	s_mov_b64 s[0:1], -1
	v_pk_mul_f32 v[14:15], v[14:15], v[20:21]
	s_nop 0
	v_pk_mul_f32 v[10:11], v[10:11], v[14:15]
	v_pk_mul_f32 v[14:15], v[16:17], v[142:143] op_sel_hi:[1,0]
	s_nop 0
	v_mul_f32_e32 v16, 0xbfb8aa3b, v14
	v_mul_f32_e32 v17, 0xbfb8aa3b, v15
	v_exp_f32_e32 v16, v16
	v_exp_f32_e32 v17, v17
	v_add_f32_e32 v16, 1.0, v16
	v_add_f32_e32 v17, 1.0, v17
	v_rcp_f32_e32 v16, v16
	v_rcp_f32_e32 v17, v17
	s_nop 0
	v_pk_mul_f32 v[14:15], v[14:15], v[16:17]
	s_nop 0
	v_pk_mul_f32 v[12:13], v[12:13], v[14:15]
	v_mul_f32_e32 v14, 0xbfb8aa3b, v6
	v_mul_f32_e32 v15, 0xbfb8aa3b, v7
	v_exp_f32_e32 v14, v14
	v_exp_f32_e32 v15, v15
	v_add_f32_e32 v14, 1.0, v14
	v_add_f32_e32 v15, 1.0, v15
	v_rcp_f32_e32 v14, v14
	v_rcp_f32_e32 v15, v15
	s_nop 0
	v_pk_mul_f32 v[6:7], v[6:7], v[14:15]
	s_nop 0
	v_pk_mul_f32 v[6:7], v[2:3], v[6:7]
	v_pk_mul_f32 v[2:3], v[8:9], v[142:143] op_sel_hi:[1,0]
	v_lshl_add_u64 v[14:15], v[18:19], 0, v[114:115]
	v_mul_f32_e32 v8, 0xbfb8aa3b, v2
	v_mul_f32_e32 v9, 0xbfb8aa3b, v3
	v_exp_f32_e32 v8, v8
	v_exp_f32_e32 v9, v9
	v_add_f32_e32 v8, 1.0, v8
	v_add_f32_e32 v9, 1.0, v9
	v_rcp_f32_e32 v8, v8
	v_rcp_f32_e32 v9, v9
	s_nop 0
	v_pk_mul_f32 v[2:3], v[2:3], v[8:9]
	s_nop 0
	v_pk_mul_f32 v[8:9], v[4:5], v[2:3]
	v_cvt_pk_bf16_f32 v2, v10, v11
	v_cvt_pk_bf16_f32 v3, v12, v13
	v_cvt_pk_bf16_f32 v4, v6, v7
	v_cvt_pk_bf16_f32 v5, v8, v9
	global_store_dwordx4 v[14:15], v[2:5], off
	s_cbranch_vccnz .LBB0_365
	s_andn2_b64 vcc, exec, s[4:5]
	s_cbranch_vccnz .LBB0_364
	s_branch .LBB0_364

; #define PG8_STAGE(bufoff, gbase, voff) do { _Pragma("unroll") for (int _i = 0; _i < 2; ++_i) \
;         __builtin_amdgcn_global_load_lds((const gunsigned*)((const gchar*)(gbase) + (voff)[_i]), (LAS unsigned*)(lds + (bufoff) + ldsw + _i * 8192), 16, 0, 0); } while (0)
; #define PG8_LDA(dst, b, h) do { _Pragma("unroll") for (int m = 0; m < 4; ++m) _Pragma("unroll") for (int k = 0; k < 2; ++k) dst[m][k] = *(const LAS bf16x8*)(lds + PG8_SA(b, h) + aoff + m * 2048 + k * 1024); } while (0)
; #define PG8_LDB(dst, b, h) do { _Pragma("unroll") for (int n = 0; n < 2; ++n) _Pragma("unroll") for (int k = 0; k < 2; ++k) dst[n][k] = *(const LAS bf16x8*)(lds + PG8_SB(b, h) + boff + n * 2048 + k * 1024); } while (0)
; #define PG8_MMA(ai, bj, At, Bt) do { __builtin_amdgcn_s_setprio(1); _Pragma("unroll") for (int m = 0; m < 4; ++m) _Pragma("unroll") for (int n = 0; n < 2; ++n) _Pragma("unroll") for (int k = 0; k < 2; ++k) \
;         acc[ai][bj][m][n] = __builtin_amdgcn_mfma_f32_16x16x32_bf16(Bt[n][k], At[m][k], acc[ai][bj][m][n], 0, 0, 0); __builtin_amdgcn_s_setprio(0); } while (0)
; #define PG8_WAIT_V(n) asm volatile("s_waitcnt vmcnt(" #n ")" ::: "memory")
; #define PG8_WAIT_L(n) asm volatile("s_waitcnt lgkmcnt(" #n ")" ::: "memory")
; #define PG8_BAR __builtin_amdgcn_s_barrier()
; #define PG8_SCHED __builtin_amdgcn_sched_barrier(0)
; template <class Epi, class Sched>
; __device__ __forceinline__ void gemm_phase(LAS unsigned char* lds, const int tid, const Gemm g, const Sched& S, const Epi& E) {
;     ...
;             PG8_LDB(B0, 0, 0); PG8_LDB(B1, 0, 1); PG8_SCHED; PG8_LDA(At, 0, 0); PG8_STAGE(PG8_SA(1, 1), a1 + hstep, voffA);
;             PG8_WAIT_V(8); PG8_WAIT_L(0); PG8_BAR; PG8_MMA(0, 0, At, B0); PG8_MMA(0, 1, At, B1); PG8_BAR; PG8_SCHED;
;             PG8_LDA(At, 0, 1); PG8_STAGE(PG8_SB(0, 0), b2, voffB); PG8_STAGE(PG8_SB(0, 1), b2 + hstep, voffB); PG8_STAGE(PG8_SA(0, 0), a2, voffA);
;             PG8_WAIT_V(8); PG8_WAIT_L(0); PG8_BAR; PG8_MMA(1, 0, At, B0); PG8_MMA(1, 1, At, B1); PG8_BAR; PG8_SCHED;
.LBB0_559:
	s_add_u32 s20, s60, 0xfffc0080
	s_addc_u32 s21, s61, -1
	s_add_i32 s29, 0, 0x10000
	s_cmp_eq_u32 s46, 12
	s_cselect_b32 s63, s9, s21
	s_cselect_b32 s62, s42, s20
	s_cselect_b32 s21, s7, s45
	s_cselect_b32 s20, s43, s44
	s_add_i32 s30, 0, 0x14000
	v_add_u32_e32 v152, s29, v165
	v_add_u32_e32 v160, s30, v165
	ds_read_b128 v[130:133], v152
	ds_read_b128 v[144:147], v152 offset:1024
	ds_read_b128 v[148:151], v152 offset:2048
	ds_read_b128 v[152:155], v152 offset:3072
	ds_read_b128 v[156:159], v160
	ds_read_b128 v[170:173], v160 offset:1024
	ds_read_b128 v[174:177], v160 offset:2048
	ds_read_b128 v[178:181], v160 offset:3072
	s_add_i32 m0, s34, 0xc000
	ds_read_b128 v[182:185], v169
	ds_read_b128 v[186:189], v169 offset:1024
	ds_read_b128 v[190:193], v169 offset:2048
	ds_read_b128 v[204:207], v169 offset:3072
	ds_read_b128 v[210:213], v169 offset:4096
	ds_read_b128 v[214:217], v169 offset:5120
	ds_read_b128 v[218:221], v169 offset:6144
	ds_read_b128 v[222:225], v169 offset:7168
	global_load_lds_dwordx4 v142, s[60:61]
	s_add_i32 m0, s34, 0xe000
	s_nop 0
	global_load_lds_dwordx4 v140, s[60:61]
	s_waitcnt vmcnt(8)
	s_waitcnt lgkmcnt(0)
	s_setprio 1
	s_barrier
	v_mfma_f32_16x16x32_bf16 v[126:129], v[130:133], v[182:185], v[126:129]
	v_mfma_f32_16x16x32_bf16 v[122:125], v[148:151], v[182:185], v[122:125]
	v_mfma_f32_16x16x32_bf16 v[118:121], v[130:133], v[190:193], v[118:121]
	v_mfma_f32_16x16x32_bf16 v[110:113], v[148:151], v[190:193], v[110:113]
	v_mfma_f32_16x16x32_bf16 v[102:105], v[130:133], v[210:213], v[102:105]
	v_mfma_f32_16x16x32_bf16 v[94:97], v[148:151], v[210:213], v[94:97]
	v_mfma_f32_16x16x32_bf16 v[86:89], v[130:133], v[218:221], v[86:89]
	v_mfma_f32_16x16x32_bf16 v[78:81], v[148:151], v[218:221], v[78:81]
	v_mfma_f32_16x16x32_bf16 v[126:129], v[144:147], v[186:189], v[126:129]
	v_mfma_f32_16x16x32_bf16 v[122:125], v[152:155], v[186:189], v[122:125]
	v_mfma_f32_16x16x32_bf16 v[118:121], v[144:147], v[204:207], v[118:121]
	v_mfma_f32_16x16x32_bf16 v[110:113], v[152:155], v[204:207], v[110:113]
	v_mfma_f32_16x16x32_bf16 v[102:105], v[144:147], v[214:217], v[102:105]
	v_mfma_f32_16x16x32_bf16 v[94:97], v[152:155], v[214:217], v[94:97]
	v_mfma_f32_16x16x32_bf16 v[86:89], v[144:147], v[222:225], v[86:89]
	v_mfma_f32_16x16x32_bf16 v[78:81], v[152:155], v[222:225], v[78:81]
	s_setprio 0
	s_setprio 1
	v_mfma_f32_16x16x32_bf16 v[114:117], v[156:159], v[182:185], v[114:117]
	v_mfma_f32_16x16x32_bf16 v[106:109], v[174:177], v[182:185], v[106:109]
	v_mfma_f32_16x16x32_bf16 v[98:101], v[156:159], v[190:193], v[98:101]
	v_mfma_f32_16x16x32_bf16 v[90:93], v[174:177], v[190:193], v[90:93]
	v_mfma_f32_16x16x32_bf16 v[82:85], v[156:159], v[210:213], v[82:85]
	v_mfma_f32_16x16x32_bf16 v[74:77], v[174:177], v[210:213], v[74:77]
	v_mfma_f32_16x16x32_bf16 v[70:73], v[156:159], v[218:221], v[70:73]
	v_mfma_f32_16x16x32_bf16 v[66:69], v[174:177], v[218:221], v[66:69]
	v_mfma_f32_16x16x32_bf16 v[114:117], v[170:173], v[186:189], v[114:117]
	v_mfma_f32_16x16x32_bf16 v[106:109], v[178:181], v[186:189], v[106:109]
	v_mfma_f32_16x16x32_bf16 v[98:101], v[170:173], v[204:207], v[98:101]
	v_mfma_f32_16x16x32_bf16 v[90:93], v[178:181], v[204:207], v[90:93]
	v_mfma_f32_16x16x32_bf16 v[82:85], v[170:173], v[214:217], v[82:85]
	v_mfma_f32_16x16x32_bf16 v[74:77], v[178:181], v[214:217], v[74:77]
	v_mfma_f32_16x16x32_bf16 v[70:73], v[170:173], v[222:225], v[70:73]
	v_mfma_f32_16x16x32_bf16 v[66:69], v[178:181], v[222:225], v[66:69]
	s_barrier
	s_setprio 0
	s_add_i32 s29, s29, s12
	s_mov_b32 m0, s29
	ds_read_b128 v[182:185], v169 offset:16384
	ds_read_b128 v[186:189], v169 offset:17408
	ds_read_b128 v[190:193], v169 offset:18432
	ds_read_b128 v[204:207], v169 offset:19456
	ds_read_b128 v[210:213], v169 offset:20480
	ds_read_b128 v[214:217], v169 offset:21504
	ds_read_b128 v[218:221], v169 offset:22528
	ds_read_b128 v[222:225], v169 offset:23552
	global_load_lds_dwordx4 v0, s[20:21]
	s_add_i32 m0, s29, 0x2000
	s_add_u32 s48, s20, 0x40000
	s_addc_u32 s49, s21, 0
	s_add_i32 s29, s30, s12
	global_load_lds_dwordx4 v134, s[20:21]
	s_mov_b32 m0, s29
	s_nop 0
	global_load_lds_dwordx4 v0, s[48:49]
	s_add_i32 m0, s29, 0x2000
	s_nop 0
	global_load_lds_dwordx4 v134, s[48:49]
	s_mov_b32 m0, s34
	s_nop 0
	global_load_lds_dwordx4 v138, s[62:63]
	s_mov_b32 m0, s35
	s_nop 0
	global_load_lds_dwordx4 v136, s[62:63]
	s_waitcnt vmcnt(8)
	s_waitcnt lgkmcnt(0)
	s_setprio 1
	s_barrier
	v_mfma_f32_16x16x32_bf16 v[62:65], v[130:133], v[182:185], v[62:65]
	v_mfma_f32_16x16x32_bf16 v[58:61], v[148:151], v[182:185], v[58:61]
	v_mfma_f32_16x16x32_bf16 v[54:57], v[130:133], v[190:193], v[54:57]
	v_mfma_f32_16x16x32_bf16 v[46:49], v[148:151], v[190:193], v[46:49]
	v_mfma_f32_16x16x32_bf16 v[38:41], v[130:133], v[210:213], v[38:41]
	v_mfma_f32_16x16x32_bf16 v[30:33], v[148:151], v[210:213], v[30:33]
	v_mfma_f32_16x16x32_bf16 v[22:25], v[130:133], v[218:221], v[22:25]
	v_mfma_f32_16x16x32_bf16 v[14:17], v[148:151], v[218:221], v[14:17]
	v_mfma_f32_16x16x32_bf16 v[62:65], v[144:147], v[186:189], v[62:65]
	v_mfma_f32_16x16x32_bf16 v[58:61], v[152:155], v[186:189], v[58:61]
	v_mfma_f32_16x16x32_bf16 v[54:57], v[144:147], v[204:207], v[54:57]
	v_mfma_f32_16x16x32_bf16 v[46:49], v[152:155], v[204:207], v[46:49]
	v_mfma_f32_16x16x32_bf16 v[38:41], v[144:147], v[214:217], v[38:41]
	v_mfma_f32_16x16x32_bf16 v[30:33], v[152:155], v[214:217], v[30:33]
	v_mfma_f32_16x16x32_bf16 v[22:25], v[144:147], v[222:225], v[22:25]
	v_mfma_f32_16x16x32_bf16 v[14:17], v[152:155], v[222:225], v[14:17]
	s_setprio 0
	s_setprio 1
	v_mfma_f32_16x16x32_bf16 v[50:53], v[156:159], v[182:185], v[50:53]
	v_mfma_f32_16x16x32_bf16 v[42:45], v[174:177], v[182:185], v[42:45]
	v_mfma_f32_16x16x32_bf16 v[34:37], v[156:159], v[190:193], v[34:37]
	v_mfma_f32_16x16x32_bf16 v[26:29], v[174:177], v[190:193], v[26:29]
	v_mfma_f32_16x16x32_bf16 v[18:21], v[156:159], v[210:213], v[18:21]
	v_mfma_f32_16x16x32_bf16 v[10:13], v[174:177], v[210:213], v[10:13]
	v_mfma_f32_16x16x32_bf16 v[6:9], v[156:159], v[218:221], v[6:9]
	v_mfma_f32_16x16x32_bf16 v[2:5], v[174:177], v[218:221], v[2:5]
	v_mfma_f32_16x16x32_bf16 v[50:53], v[170:173], v[186:189], v[50:53]
	v_mfma_f32_16x16x32_bf16 v[42:45], v[178:181], v[186:189], v[42:45]
	v_mfma_f32_16x16x32_bf16 v[34:37], v[170:173], v[204:207], v[34:37]
	v_mfma_f32_16x16x32_bf16 v[26:29], v[178:181], v[204:207], v[26:29]
	v_mfma_f32_16x16x32_bf16 v[18:21], v[170:173], v[214:217], v[18:21]
	v_mfma_f32_16x16x32_bf16 v[10:13], v[178:181], v[214:217], v[10:13]
	v_mfma_f32_16x16x32_bf16 v[6:9], v[170:173], v[222:225], v[6:9]
	v_mfma_f32_16x16x32_bf16 v[2:5], v[178:181], v[222:225], v[2:5]
	s_barrier
; #define PG8_STAGE(bufoff, gbase, voff) do { _Pragma("unroll") for (int _i = 0; _i < 2; ++_i) \
;         __builtin_amdgcn_global_load_lds((const gunsigned*)((const gchar*)(gbase) + (voff)[_i]), (LAS unsigned*)(lds + (bufoff) + ldsw + _i * 8192), 16, 0, 0); } while (0)
; #define PG8_LDA(dst, b, h) do { _Pragma("unroll") for (int m = 0; m < 4; ++m) _Pragma("unroll") for (int k = 0; k < 2; ++k) dst[m][k] = *(const LAS bf16x8*)(lds + PG8_SA(b, h) + aoff + m * 2048 + k * 1024); } while (0)
; #define PG8_LDB(dst, b, h) do { _Pragma("unroll") for (int n = 0; n < 2; ++n) _Pragma("unroll") for (int k = 0; k < 2; ++k) dst[n][k] = *(const LAS bf16x8*)(lds + PG8_SB(b, h) + boff + n * 2048 + k * 1024); } while (0)
; #define PG8_MMA(ai, bj, At, Bt) do { __builtin_amdgcn_s_setprio(1); _Pragma("unroll") for (int m = 0; m < 4; ++m) _Pragma("unroll") for (int n = 0; n < 2; ++n) _Pragma("unroll") for (int k = 0; k < 2; ++k) \
;         acc[ai][bj][m][n] = __builtin_amdgcn_mfma_f32_16x16x32_bf16(Bt[n][k], At[m][k], acc[ai][bj][m][n], 0, 0, 0); __builtin_amdgcn_s_setprio(0); } while (0)
; #define PG8_WAIT_V(n) asm volatile("s_waitcnt vmcnt(" #n ")" ::: "memory")
; #define PG8_WAIT_L(n) asm volatile("s_waitcnt lgkmcnt(" #n ")" ::: "memory")
; #define PG8_BAR __builtin_amdgcn_s_barrier()
; #define PG8_SCHED __builtin_amdgcn_sched_barrier(0)
; template <class Epi, class Sched>
; __device__ __forceinline__ void gemm_phase(LAS unsigned char* lds, const int tid, const Gemm g, const Sched& S, const Epi& E) {
;     ...
;             PG8_LDB(B0, 1, 0); PG8_LDB(B1, 1, 1); PG8_SCHED; PG8_LDA(At, 1, 0); PG8_STAGE(PG8_SA(0, 1), a2 + hstep, voffA);
;             PG8_WAIT_V(8); PG8_WAIT_L(0); PG8_BAR; PG8_MMA(0, 0, At, B0); PG8_MMA(0, 1, At, B1); PG8_BAR; PG8_SCHED;
;             PG8_LDA(At, 1, 1); PG8_STAGE(PG8_SB(1, 0), b3, voffB); PG8_STAGE(PG8_SB(1, 1), b3 + hstep, voffB); PG8_STAGE(PG8_SA(1, 0), a3, voffA);
;             PG8_WAIT_V(8); PG8_WAIT_L(0); PG8_BAR; PG8_MMA(1, 0, At, B0); PG8_MMA(1, 1, At, B1); PG8_BAR; PG8_SCHED;
;         }
;         if (wr == 0) PG8_BAR;
	s_setprio 0
	s_add_i32 s29, 0, 0x18000
	s_add_i32 s30, 0, 0x1c000
	v_add_u32_e32 v152, s29, v165
	v_add_u32_e32 v162, s30, v165
	ds_read_b128 v[130:133], v152
	ds_read_b128 v[144:147], v152 offset:1024
	ds_read_b128 v[148:151], v152 offset:2048
	ds_read_b128 v[152:155], v152 offset:3072
	ds_read_b128 v[156:159], v162
	ds_read_b128 v[170:173], v162 offset:1024
	ds_read_b128 v[174:177], v162 offset:2048
	ds_read_b128 v[178:181], v162 offset:3072
	s_add_u32 s48, s62, 0x40000
	s_addc_u32 s49, s63, 0
	s_mov_b32 m0, s36
	ds_read_b128 v[182:185], v169 offset:32768
	ds_read_b128 v[186:189], v169 offset:33792
	ds_read_b128 v[190:193], v169 offset:34816
	ds_read_b128 v[204:207], v169 offset:35840
	ds_read_b128 v[210:213], v169 offset:36864
	ds_read_b128 v[214:217], v169 offset:37888
	ds_read_b128 v[218:221], v169 offset:38912
	ds_read_b128 v[222:225], v169 offset:39936
	global_load_lds_dwordx4 v138, s[48:49]
	s_mov_b32 m0, s37
	s_nop 0
	global_load_lds_dwordx4 v136, s[48:49]
	s_waitcnt vmcnt(8)
	s_waitcnt lgkmcnt(0)
	s_setprio 1
	s_barrier
	v_mfma_f32_16x16x32_bf16 v[126:129], v[130:133], v[182:185], v[126:129]
	v_mfma_f32_16x16x32_bf16 v[122:125], v[148:151], v[182:185], v[122:125]
	v_mfma_f32_16x16x32_bf16 v[118:121], v[130:133], v[190:193], v[118:121]
	v_mfma_f32_16x16x32_bf16 v[110:113], v[148:151], v[190:193], v[110:113]
	v_mfma_f32_16x16x32_bf16 v[102:105], v[130:133], v[210:213], v[102:105]
	v_mfma_f32_16x16x32_bf16 v[94:97], v[148:151], v[210:213], v[94:97]
	v_mfma_f32_16x16x32_bf16 v[86:89], v[130:133], v[218:221], v[86:89]
	v_mfma_f32_16x16x32_bf16 v[78:81], v[148:151], v[218:221], v[78:81]
	v_mfma_f32_16x16x32_bf16 v[126:129], v[144:147], v[186:189], v[126:129]
	v_mfma_f32_16x16x32_bf16 v[122:125], v[152:155], v[186:189], v[122:125]
	v_mfma_f32_16x16x32_bf16 v[118:121], v[144:147], v[204:207], v[118:121]
	v_mfma_f32_16x16x32_bf16 v[110:113], v[152:155], v[204:207], v[110:113]
	v_mfma_f32_16x16x32_bf16 v[102:105], v[144:147], v[214:217], v[102:105]
	v_mfma_f32_16x16x32_bf16 v[94:97], v[152:155], v[214:217], v[94:97]
	v_mfma_f32_16x16x32_bf16 v[86:89], v[144:147], v[222:225], v[86:89]
	v_mfma_f32_16x16x32_bf16 v[78:81], v[152:155], v[222:225], v[78:81]
	s_setprio 0
	s_setprio 1
	v_mfma_f32_16x16x32_bf16 v[114:117], v[156:159], v[182:185], v[114:117]
	v_mfma_f32_16x16x32_bf16 v[106:109], v[174:177], v[182:185], v[106:109]
	v_mfma_f32_16x16x32_bf16 v[98:101], v[156:159], v[190:193], v[98:101]
	v_mfma_f32_16x16x32_bf16 v[90:93], v[174:177], v[190:193], v[90:93]
	v_mfma_f32_16x16x32_bf16 v[82:85], v[156:159], v[210:213], v[82:85]
	v_mfma_f32_16x16x32_bf16 v[74:77], v[174:177], v[210:213], v[74:77]
	v_mfma_f32_16x16x32_bf16 v[70:73], v[156:159], v[218:221], v[70:73]
	v_mfma_f32_16x16x32_bf16 v[66:69], v[174:177], v[218:221], v[66:69]
	v_mfma_f32_16x16x32_bf16 v[114:117], v[170:173], v[186:189], v[114:117]
	v_mfma_f32_16x16x32_bf16 v[106:109], v[178:181], v[186:189], v[106:109]
	v_mfma_f32_16x16x32_bf16 v[98:101], v[170:173], v[204:207], v[98:101]
	v_mfma_f32_16x16x32_bf16 v[90:93], v[178:181], v[204:207], v[90:93]
	v_mfma_f32_16x16x32_bf16 v[82:85], v[170:173], v[214:217], v[82:85]
	v_mfma_f32_16x16x32_bf16 v[74:77], v[178:181], v[214:217], v[74:77]
	v_mfma_f32_16x16x32_bf16 v[70:73], v[170:173], v[222:225], v[70:73]
	v_mfma_f32_16x16x32_bf16 v[66:69], v[178:181], v[222:225], v[66:69]
	s_barrier
	s_setprio 0
	s_add_i32 s29, s29, s12
	s_mov_b32 m0, s29
	ds_read_b128 v[182:185], v169 offset:49152
	ds_read_b128 v[186:189], v169 offset:50176
	ds_read_b128 v[190:193], v169 offset:51200
	ds_read_b128 v[204:207], v169 offset:52224
	ds_read_b128 v[210:213], v169 offset:53248
	ds_read_b128 v[214:217], v169 offset:54272
	ds_read_b128 v[218:221], v169 offset:55296
	ds_read_b128 v[222:225], v169 offset:56320
	global_load_lds_dwordx4 v161, s[20:21]
	s_add_i32 m0, s29, 0x2000
	s_add_i32 s29, s30, s12
	global_load_lds_dwordx4 v195, s[20:21]
	s_add_u32 s20, s20, 0x40080
	s_addc_u32 s21, s21, 0
	s_mov_b32 m0, s29
	s_nop 0
	global_load_lds_dwordx4 v0, s[20:21]
	s_add_i32 m0, s29, 0x2000
	s_nop 0
	global_load_lds_dwordx4 v134, s[20:21]
	s_mov_b32 m0, s38
	s_nop 0
	global_load_lds_dwordx4 v201, s[62:63]
	s_mov_b32 m0, s39
	s_nop 0
	global_load_lds_dwordx4 v227, s[62:63]
	s_waitcnt vmcnt(8)
	s_waitcnt lgkmcnt(0)
	s_setprio 1
	s_barrier
	v_mfma_f32_16x16x32_bf16 v[62:65], v[130:133], v[182:185], v[62:65]
	v_mfma_f32_16x16x32_bf16 v[58:61], v[148:151], v[182:185], v[58:61]
	v_mfma_f32_16x16x32_bf16 v[54:57], v[130:133], v[190:193], v[54:57]
	v_mfma_f32_16x16x32_bf16 v[46:49], v[148:151], v[190:193], v[46:49]
	v_mfma_f32_16x16x32_bf16 v[38:41], v[130:133], v[210:213], v[38:41]
	v_mfma_f32_16x16x32_bf16 v[30:33], v[148:151], v[210:213], v[30:33]
	v_mfma_f32_16x16x32_bf16 v[22:25], v[130:133], v[218:221], v[22:25]
	v_mfma_f32_16x16x32_bf16 v[14:17], v[148:151], v[218:221], v[14:17]
	v_mfma_f32_16x16x32_bf16 v[62:65], v[144:147], v[186:189], v[62:65]
	v_mfma_f32_16x16x32_bf16 v[58:61], v[152:155], v[186:189], v[58:61]
	v_mfma_f32_16x16x32_bf16 v[54:57], v[144:147], v[204:207], v[54:57]
	v_mfma_f32_16x16x32_bf16 v[46:49], v[152:155], v[204:207], v[46:49]
	v_mfma_f32_16x16x32_bf16 v[38:41], v[144:147], v[214:217], v[38:41]
	v_mfma_f32_16x16x32_bf16 v[30:33], v[152:155], v[214:217], v[30:33]
	v_mfma_f32_16x16x32_bf16 v[22:25], v[144:147], v[222:225], v[22:25]
	v_mfma_f32_16x16x32_bf16 v[14:17], v[152:155], v[222:225], v[14:17]
	s_setprio 0
	s_setprio 1
	v_mfma_f32_16x16x32_bf16 v[50:53], v[156:159], v[182:185], v[50:53]
	v_mfma_f32_16x16x32_bf16 v[42:45], v[174:177], v[182:185], v[42:45]
	v_mfma_f32_16x16x32_bf16 v[34:37], v[156:159], v[190:193], v[34:37]
	v_mfma_f32_16x16x32_bf16 v[26:29], v[174:177], v[190:193], v[26:29]
	v_mfma_f32_16x16x32_bf16 v[18:21], v[156:159], v[210:213], v[18:21]
	v_mfma_f32_16x16x32_bf16 v[10:13], v[174:177], v[210:213], v[10:13]
	v_mfma_f32_16x16x32_bf16 v[6:9], v[156:159], v[218:221], v[6:9]
	v_mfma_f32_16x16x32_bf16 v[2:5], v[174:177], v[218:221], v[2:5]
	v_mfma_f32_16x16x32_bf16 v[50:53], v[170:173], v[186:189], v[50:53]
	v_mfma_f32_16x16x32_bf16 v[42:45], v[178:181], v[186:189], v[42:45]
	v_mfma_f32_16x16x32_bf16 v[34:37], v[170:173], v[204:207], v[34:37]
	v_mfma_f32_16x16x32_bf16 v[26:29], v[178:181], v[204:207], v[26:29]
	v_mfma_f32_16x16x32_bf16 v[18:21], v[170:173], v[214:217], v[18:21]
	v_mfma_f32_16x16x32_bf16 v[10:13], v[178:181], v[214:217], v[10:13]
	v_mfma_f32_16x16x32_bf16 v[6:9], v[170:173], v[222:225], v[6:9]
	v_mfma_f32_16x16x32_bf16 v[2:5], v[178:181], v[222:225], v[2:5]
	s_barrier
	s_setprio 0
	s_add_i32 s46, s46, 2
	s_add_u32 s44, s44, 0x100
	s_addc_u32 s45, s45, 0
	s_add_u32 s60, s60, 0x100
	s_addc_u32 s61, s61, 0
	s_cmp_gt_u32 s46, 13
	s_cbranch_scc0 .LBB0_559
	s_and_b64 vcc, exec, s[4:5]
	s_cbranch_vccz .LBB0_562
	s_and_b64 vcc, exec, s[2:3]
	s_cbranch_vccnz .LBB0_562
	s_barrier

; __device__ __forceinline__ unsigned pk2(float lo, float hi) { f32x2 v = {lo, hi}; bf16x2_t b = __builtin_convertvector(v, bf16x2_t); return __builtin_bit_cast(unsigned, b); }
;     __device__ __forceinline__ void operator()(const f32x4 (&acc)[2][2][4][2], const Unit& u, int wr, int wc, int fr, int fq, LAS unsigned char* lds, int tid) const {
;     ...
;         const float tsc = !qscale ? 1.0f : (u.pn == 3 || u.pn == 4) ? 0.125f * LOG2E : (u.pn == 6 || u.pn == 7) ? 0.08838834764831845f * LOG2E : 1.0f;
;     ...
;         for (int ai = 0; ai < 2; ++ai)
; #pragma unroll
;             for (int m = 0; m < 4; ++m) { const size_t row = (size_t)(row0 + ai * HALF + m * 16); const float rs = rsv[ai][m]; gbf16* rowp = O + row * ldc + col0;
; #pragma unroll
;                 for (int bj = 0; bj < 2; ++bj) { const f32x4 v0 = acc[ai][bj][m][0] * rs, v1 = acc[ai][bj][m][1] * rs;
;                     u32x4 w; w.x = pk2(v0[0], v0[1]); w.y = pk2(v0[2], v0[3]); w.z = pk2(v1[0], v1[1]); w.w = pk2(v1[2], v1[3]);
;                     *(gu32x4*)(rowp + bj * HALF) = w; } }
.Lk3_rs_hit:
	s_andn2_b64 vcc, exec, s[2:3]
	v_mul_f32_e32 v174, v159, v226
	v_mul_f32_e32 v172, v159, v236
	v_mul_f32_e32 v170, v159, v237
	v_mul_f32_e32 v168, v159, v244
	v_mul_f32_e32 v166, v159, v245
	v_mul_f32_e32 v164, v159, v246
	v_mul_f32_e32 v162, v159, v247
	v_mul_f32_e32 v130, v159, v248
	v_mov_b64_e32 v[132:133], s[96:97]
	v_mad_i64_i32 v[160:161], s[20:21], v160, s33, v[132:133]
	v_ashrrev_i32_e32 v159, 31, v158
	v_lshlrev_b64 v[158:159], 1, v[158:159]
	v_pk_mul_f32 v[128:129], v[128:129], v[174:175] op_sel_hi:[1,0]
	v_pk_mul_f32 v[126:127], v[126:127], v[174:175] op_sel_hi:[1,0]
	v_pk_mul_f32 v[176:177], v[124:125], v[174:175] op_sel_hi:[1,0]
	v_pk_mul_f32 v[124:125], v[122:123], v[174:175] op_sel_hi:[1,0]
	v_lshl_add_u64 v[160:161], v[160:161], 0, v[158:159]
	v_cvt_pk_bf16_f32 v122, v126, v127
	v_cvt_pk_bf16_f32 v123, v128, v129
	v_cvt_pk_bf16_f32 v124, v124, v125
	v_cvt_pk_bf16_f32 v125, v176, v177
	global_store_dwordx4 v[160:161], v[122:125], off
	v_pk_mul_f32 v[116:117], v[116:117], v[174:175] op_sel_hi:[1,0]
	v_pk_mul_f32 v[114:115], v[114:115], v[174:175] op_sel_hi:[1,0]
	v_pk_mul_f32 v[122:123], v[108:109], v[174:175] op_sel_hi:[1,0]
	v_pk_mul_f32 v[108:109], v[106:107], v[174:175] op_sel_hi:[1,0]
	v_cvt_pk_bf16_f32 v106, v114, v115
	v_cvt_pk_bf16_f32 v107, v116, v117
	v_cvt_pk_bf16_f32 v108, v108, v109
	v_cvt_pk_bf16_f32 v109, v122, v123
	global_store_dwordx4 v[160:161], v[106:109], off offset:256
	v_pk_mul_f32 v[112:113], v[112:113], v[172:173] op_sel_hi:[1,0]
	v_pk_mul_f32 v[110:111], v[110:111], v[172:173] op_sel_hi:[1,0]
	v_mad_i64_i32 v[106:107], s[20:21], v156, s33, v[132:133]
	v_lshl_add_u64 v[114:115], v[106:107], 0, v[158:159]
	v_pk_mul_f32 v[108:109], v[120:121], v[172:173] op_sel_hi:[1,0]
	v_pk_mul_f32 v[106:107], v[118:119], v[172:173] op_sel_hi:[1,0]
	v_pk_mul_f32 v[100:101], v[100:101], v[172:173] op_sel_hi:[1,0]
	v_cvt_pk_bf16_f32 v106, v106, v107
	v_cvt_pk_bf16_f32 v107, v108, v109
	v_cvt_pk_bf16_f32 v108, v110, v111
	v_cvt_pk_bf16_f32 v109, v112, v113
	global_store_dwordx4 v[114:115], v[106:109], off
	v_pk_mul_f32 v[98:99], v[98:99], v[172:173] op_sel_hi:[1,0]
	v_pk_mul_f32 v[96:97], v[96:97], v[170:171] op_sel_hi:[1,0]
	v_pk_mul_f32 v[106:107], v[92:93], v[172:173] op_sel_hi:[1,0]
	v_pk_mul_f32 v[92:93], v[90:91], v[172:173] op_sel_hi:[1,0]
	v_cvt_pk_bf16_f32 v90, v98, v99
	v_cvt_pk_bf16_f32 v91, v100, v101
	v_cvt_pk_bf16_f32 v92, v92, v93
	v_cvt_pk_bf16_f32 v93, v106, v107
	global_store_dwordx4 v[114:115], v[90:93], off offset:256
	v_pk_mul_f32 v[94:95], v[94:95], v[170:171] op_sel_hi:[1,0]
	v_pk_mul_f32 v[84:85], v[84:85], v[170:171] op_sel_hi:[1,0]
	v_mad_i64_i32 v[90:91], s[20:21], v154, s33, v[132:133]
	v_lshl_add_u64 v[98:99], v[90:91], 0, v[158:159]
	v_pk_mul_f32 v[92:93], v[104:105], v[170:171] op_sel_hi:[1,0]
	v_pk_mul_f32 v[90:91], v[102:103], v[170:171] op_sel_hi:[1,0]
	v_pk_mul_f32 v[82:83], v[82:83], v[170:171] op_sel_hi:[1,0]
	v_cvt_pk_bf16_f32 v90, v90, v91
	v_cvt_pk_bf16_f32 v91, v92, v93
	v_cvt_pk_bf16_f32 v92, v94, v95
	v_cvt_pk_bf16_f32 v93, v96, v97
	global_store_dwordx4 v[98:99], v[90:93], off
	v_pk_mul_f32 v[80:81], v[80:81], v[168:169] op_sel_hi:[1,0]
	v_pk_mul_f32 v[78:79], v[78:79], v[168:169] op_sel_hi:[1,0]
	v_pk_mul_f32 v[90:91], v[76:77], v[170:171] op_sel_hi:[1,0]
	v_pk_mul_f32 v[76:77], v[74:75], v[170:171] op_sel_hi:[1,0]
	v_cvt_pk_bf16_f32 v74, v82, v83
	v_cvt_pk_bf16_f32 v75, v84, v85
	v_cvt_pk_bf16_f32 v76, v76, v77
	v_cvt_pk_bf16_f32 v77, v90, v91
	global_store_dwordx4 v[98:99], v[74:77], off offset:256
	v_pk_mul_f32 v[72:73], v[72:73], v[168:169] op_sel_hi:[1,0]
	v_pk_mul_f32 v[70:71], v[70:71], v[168:169] op_sel_hi:[1,0]
	v_mad_i64_i32 v[74:75], s[20:21], v152, s33, v[132:133]
	v_lshl_add_u64 v[82:83], v[74:75], 0, v[158:159]
	v_pk_mul_f32 v[76:77], v[88:89], v[168:169] op_sel_hi:[1,0]
	v_pk_mul_f32 v[74:75], v[86:87], v[168:169] op_sel_hi:[1,0]
	v_pk_mul_f32 v[64:65], v[64:65], v[166:167] op_sel_hi:[1,0]
	v_cvt_pk_bf16_f32 v74, v74, v75
	v_cvt_pk_bf16_f32 v75, v76, v77
	v_cvt_pk_bf16_f32 v76, v78, v79
	v_cvt_pk_bf16_f32 v77, v80, v81
	global_store_dwordx4 v[82:83], v[74:77], off
	v_pk_mul_f32 v[62:63], v[62:63], v[166:167] op_sel_hi:[1,0]
; __device__ __forceinline__ unsigned pk2(float lo, float hi) { f32x2 v = {lo, hi}; bf16x2_t b = __builtin_convertvector(v, bf16x2_t); return __builtin_bit_cast(unsigned, b); }
; #define PG8_BAR __builtin_amdgcn_s_barrier()
;     __device__ __forceinline__ void operator()(const f32x4 (&acc)[2][2][4][2], const Unit& u, int wr, int wc, int fr, int fq, LAS unsigned char* lds, int tid) const {
;     ...
;         for (int ai = 0; ai < 2; ++ai)
; #pragma unroll
;             for (int m = 0; m < 4; ++m) { const size_t row = (size_t)(row0 + ai * HALF + m * 16); const float rs = rsv[ai][m]; gbf16* rowp = O + row * ldc + col0;
; #pragma unroll
;                 for (int bj = 0; bj < 2; ++bj) { const f32x4 v0 = acc[ai][bj][m][0] * rs, v1 = acc[ai][bj][m][1] * rs;
;                     u32x4 w; w.x = pk2(v0[0], v0[1]); w.y = pk2(v0[2], v0[3]); w.z = pk2(v1[0], v1[1]); w.w = pk2(v1[2], v1[3]);
;                     *(gu32x4*)(rowp + bj * HALF) = w; } }
; template <class Epi, class Sched>
; __device__ __forceinline__ void gemm_phase(LAS unsigned char* lds, const int tid, const Gemm g, const Sched& S, const Epi& E) {
;     ...
;         cur = nxt; cA = nA; cB = nB; ++ui;
;         if (wr == 1) PG8_BAR;
	v_pk_mul_f32 v[52:53], v[52:53], v[166:167] op_sel_hi:[1,0]
	v_pk_mul_f32 v[74:75], v[68:69], v[168:169] op_sel_hi:[1,0]
	v_pk_mul_f32 v[68:69], v[66:67], v[168:169] op_sel_hi:[1,0]
	v_cvt_pk_bf16_f32 v66, v70, v71
	v_cvt_pk_bf16_f32 v67, v72, v73
	v_cvt_pk_bf16_f32 v68, v68, v69
	v_cvt_pk_bf16_f32 v69, v74, v75
	global_store_dwordx4 v[82:83], v[66:69], off offset:256
	v_pk_mul_f32 v[50:51], v[50:51], v[166:167] op_sel_hi:[1,0]
	v_pk_mul_f32 v[48:49], v[48:49], v[164:165] op_sel_hi:[1,0]
	v_mad_i64_i32 v[66:67], s[20:21], v150, s33, v[132:133]
	v_pk_mul_f32 v[68:69], v[60:61], v[166:167] op_sel_hi:[1,0]
	v_pk_mul_f32 v[60:61], v[58:59], v[166:167] op_sel_hi:[1,0]
	v_lshl_add_u64 v[66:67], v[66:67], 0, v[158:159]
	v_cvt_pk_bf16_f32 v58, v62, v63
	v_cvt_pk_bf16_f32 v59, v64, v65
	v_cvt_pk_bf16_f32 v60, v60, v61
	v_cvt_pk_bf16_f32 v61, v68, v69
	global_store_dwordx4 v[66:67], v[58:61], off
	v_pk_mul_f32 v[46:47], v[46:47], v[164:165] op_sel_hi:[1,0]
	v_pk_mul_f32 v[36:37], v[36:37], v[164:165] op_sel_hi:[1,0]
	v_pk_mul_f32 v[58:59], v[44:45], v[166:167] op_sel_hi:[1,0]
	v_pk_mul_f32 v[44:45], v[42:43], v[166:167] op_sel_hi:[1,0]
	v_cvt_pk_bf16_f32 v42, v50, v51
	v_cvt_pk_bf16_f32 v43, v52, v53
	v_cvt_pk_bf16_f32 v44, v44, v45
	v_cvt_pk_bf16_f32 v45, v58, v59
	global_store_dwordx4 v[66:67], v[42:45], off offset:256
	v_pk_mul_f32 v[34:35], v[34:35], v[164:165] op_sel_hi:[1,0]
	v_pk_mul_f32 v[32:33], v[32:33], v[162:163] op_sel_hi:[1,0]
	v_mad_i64_i32 v[42:43], s[20:21], v148, s33, v[132:133]
	v_lshl_add_u64 v[50:51], v[42:43], 0, v[158:159]
	v_pk_mul_f32 v[44:45], v[56:57], v[164:165] op_sel_hi:[1,0]
	v_pk_mul_f32 v[42:43], v[54:55], v[164:165] op_sel_hi:[1,0]
	v_pk_mul_f32 v[30:31], v[30:31], v[162:163] op_sel_hi:[1,0]
	v_cvt_pk_bf16_f32 v42, v42, v43
	v_cvt_pk_bf16_f32 v43, v44, v45
	v_cvt_pk_bf16_f32 v44, v46, v47
	v_cvt_pk_bf16_f32 v45, v48, v49
	global_store_dwordx4 v[50:51], v[42:45], off
	v_pk_mul_f32 v[20:21], v[20:21], v[162:163] op_sel_hi:[1,0]
	v_pk_mul_f32 v[18:19], v[18:19], v[162:163] op_sel_hi:[1,0]
	v_pk_mul_f32 v[42:43], v[28:29], v[164:165] op_sel_hi:[1,0]
	v_pk_mul_f32 v[28:29], v[26:27], v[164:165] op_sel_hi:[1,0]
	v_cvt_pk_bf16_f32 v26, v34, v35
	v_cvt_pk_bf16_f32 v27, v36, v37
	v_cvt_pk_bf16_f32 v28, v28, v29
	v_cvt_pk_bf16_f32 v29, v42, v43
	global_store_dwordx4 v[50:51], v[26:29], off offset:256
	v_pk_mul_f32 v[16:17], v[16:17], v[130:131] op_sel_hi:[1,0]
	v_pk_mul_f32 v[14:15], v[14:15], v[130:131] op_sel_hi:[1,0]
	v_mad_i64_i32 v[26:27], s[20:21], v146, s33, v[132:133]
	v_lshl_add_u64 v[34:35], v[26:27], 0, v[158:159]
	v_pk_mul_f32 v[28:29], v[40:41], v[162:163] op_sel_hi:[1,0]
	v_pk_mul_f32 v[26:27], v[38:39], v[162:163] op_sel_hi:[1,0]
	v_pk_mul_f32 v[8:9], v[8:9], v[130:131] op_sel_hi:[1,0]
	v_cvt_pk_bf16_f32 v26, v26, v27
	v_cvt_pk_bf16_f32 v27, v28, v29
	v_cvt_pk_bf16_f32 v28, v30, v31
	v_cvt_pk_bf16_f32 v29, v32, v33
	global_store_dwordx4 v[34:35], v[26:29], off
	v_pk_mul_f32 v[6:7], v[6:7], v[130:131] op_sel_hi:[1,0]
	s_nop 0
	v_pk_mul_f32 v[26:27], v[12:13], v[162:163] op_sel_hi:[1,0]
	v_pk_mul_f32 v[12:13], v[10:11], v[162:163] op_sel_hi:[1,0]
	v_cvt_pk_bf16_f32 v10, v18, v19
	v_cvt_pk_bf16_f32 v11, v20, v21
	v_cvt_pk_bf16_f32 v12, v12, v13
	v_cvt_pk_bf16_f32 v13, v26, v27
	global_store_dwordx4 v[34:35], v[10:13], off offset:256
	s_nop 1
	v_mad_i64_i32 v[10:11], s[20:21], v144, s33, v[132:133]
	v_lshl_add_u64 v[18:19], v[10:11], 0, v[158:159]
	v_pk_mul_f32 v[12:13], v[24:25], v[130:131] op_sel_hi:[1,0]
	v_pk_mul_f32 v[10:11], v[22:23], v[130:131] op_sel_hi:[1,0]
	s_mov_b64 s[20:21], -1
	v_cvt_pk_bf16_f32 v10, v10, v11
	v_cvt_pk_bf16_f32 v11, v12, v13
	v_cvt_pk_bf16_f32 v12, v14, v15
	v_cvt_pk_bf16_f32 v13, v16, v17
	global_store_dwordx4 v[18:19], v[10:13], off
	s_nop 1
	v_pk_mul_f32 v[10:11], v[4:5], v[130:131] op_sel_hi:[1,0]
	v_pk_mul_f32 v[4:5], v[2:3], v[130:131] op_sel_hi:[1,0]
	v_cvt_pk_bf16_f32 v2, v6, v7
	v_cvt_pk_bf16_f32 v3, v8, v9
	v_cvt_pk_bf16_f32 v4, v4, v5
	v_cvt_pk_bf16_f32 v5, v10, v11
	global_store_dwordx4 v[18:19], v[2:5], off offset:256
	s_cbranch_vccnz .LBB0_555
	s_andn2_b64 vcc, exec, s[0:1]
	s_cbranch_vccnz .LBB0_554
	s_branch .LBB0_554

; #define PG8_STAGE(bufoff, gbase, voff) do { _Pragma("unroll") for (int _i = 0; _i < 2; ++_i) \
;         __builtin_amdgcn_global_load_lds((const gunsigned*)((const gchar*)(gbase) + (voff)[_i]), (LAS unsigned*)(lds + (bufoff) + ldsw + _i * 8192), 16, 0, 0); } while (0)
; #define PG8_LDA(dst, b, h) do { _Pragma("unroll") for (int m = 0; m < 4; ++m) _Pragma("unroll") for (int k = 0; k < 2; ++k) dst[m][k] = *(const LAS bf16x8*)(lds + PG8_SA(b, h) + aoff + m * 2048 + k * 1024); } while (0)
; #define PG8_LDB(dst, b, h) do { _Pragma("unroll") for (int n = 0; n < 2; ++n) _Pragma("unroll") for (int k = 0; k < 2; ++k) dst[n][k] = *(const LAS bf16x8*)(lds + PG8_SB(b, h) + boff + n * 2048 + k * 1024); } while (0)
; #define PG8_MMA(ai, bj, At, Bt) do { __builtin_amdgcn_s_setprio(1); _Pragma("unroll") for (int m = 0; m < 4; ++m) _Pragma("unroll") for (int n = 0; n < 2; ++n) _Pragma("unroll") for (int k = 0; k < 2; ++k) \
;         acc[ai][bj][m][n] = __builtin_amdgcn_mfma_f32_16x16x32_bf16(Bt[n][k], At[m][k], acc[ai][bj][m][n], 0, 0, 0); __builtin_amdgcn_s_setprio(0); } while (0)
; #define PG8_WAIT_V(n) asm volatile("s_waitcnt vmcnt(" #n ")" ::: "memory")
; #define PG8_WAIT_L(n) asm volatile("s_waitcnt lgkmcnt(" #n ")" ::: "memory")
; #define PG8_BAR __builtin_amdgcn_s_barrier()
; #define PG8_SCHED __builtin_amdgcn_sched_barrier(0)
; template <class Epi, class Sched>
; __device__ __forceinline__ void gemm_phase(LAS unsigned char* lds, const int tid, const Gemm g, const Sched& S, const Epi& E) {
;     ...
;             PG8_LDB(B0, 0, 0); PG8_LDB(B1, 0, 1); PG8_SCHED; PG8_LDA(At, 0, 0); PG8_STAGE(PG8_SA(1, 1), a1 + hstep, voffA);
;             PG8_WAIT_V(8); PG8_WAIT_L(0); PG8_BAR; PG8_MMA(0, 0, At, B0); PG8_MMA(0, 1, At, B1); PG8_BAR; PG8_SCHED;
;             PG8_LDA(At, 0, 1); PG8_STAGE(PG8_SB(0, 0), b2, voffB); PG8_STAGE(PG8_SB(0, 1), b2 + hstep, voffB); PG8_STAGE(PG8_SA(0, 0), a2, voffA);
;             PG8_WAIT_V(8); PG8_WAIT_L(0); PG8_BAR; PG8_MMA(1, 0, At, B0); PG8_MMA(1, 1, At, B1); PG8_BAR; PG8_SCHED;
.LBB0_647:
	s_add_u32 s20, s58, 0xfffc0080
	s_addc_u32 s21, s59, -1
	s_add_i32 s42, 0, 0x10000
	s_cmp_eq_u32 s41, 12
	s_cselect_b32 s61, s9, s21
	s_cselect_b32 s60, s37, s20
	v_add_u32_e32 v140, s42, v143
	s_cselect_b32 s21, s7, s40
	s_cselect_b32 s20, s38, s39
	s_add_i32 s44, 0, 0x14000
	ds_read_b128 v[146:149], v140
	ds_read_b128 v[150:153], v140 offset:1024
	ds_read_b128 v[154:157], v140 offset:2048
	ds_read_b128 v[158:161], v140 offset:3072
	v_add_u32_e32 v140, s44, v143
	ds_read_b128 v[162:165], v140
	ds_read_b128 v[166:169], v140 offset:1024
	ds_read_b128 v[170:173], v140 offset:2048
	ds_read_b128 v[174:177], v140 offset:3072
	s_add_i32 m0, s23, 0xc000
	ds_read_b128 v[178:181], v145
	ds_read_b128 v[182:185], v145 offset:1024
	ds_read_b128 v[186:189], v145 offset:2048
	ds_read_b128 v[190:193], v145 offset:3072
	ds_read_b128 v[204:207], v145 offset:4096
	ds_read_b128 v[208:211], v145 offset:5120
	ds_read_b128 v[212:215], v145 offset:6144
	ds_read_b128 v[216:219], v145 offset:7168
	global_load_lds_dwordx4 v138, s[58:59]
	s_add_i32 m0, s23, 0xe000
	s_nop 0
	global_load_lds_dwordx4 v136, s[58:59]
	s_waitcnt vmcnt(8)
	s_waitcnt lgkmcnt(0)
	s_setprio 1
	s_barrier
	v_mfma_f32_16x16x32_bf16 v[126:129], v[146:149], v[178:181], v[126:129]
	v_mfma_f32_16x16x32_bf16 v[122:125], v[154:157], v[178:181], v[122:125]
	v_mfma_f32_16x16x32_bf16 v[110:113], v[146:149], v[186:189], v[110:113]
	v_mfma_f32_16x16x32_bf16 v[106:109], v[154:157], v[186:189], v[106:109]
	v_mfma_f32_16x16x32_bf16 v[94:97], v[146:149], v[204:207], v[94:97]
	v_mfma_f32_16x16x32_bf16 v[90:93], v[154:157], v[204:207], v[90:93]
	v_mfma_f32_16x16x32_bf16 v[78:81], v[146:149], v[212:215], v[78:81]
	v_mfma_f32_16x16x32_bf16 v[74:77], v[154:157], v[212:215], v[74:77]
	v_mfma_f32_16x16x32_bf16 v[126:129], v[150:153], v[182:185], v[126:129]
	v_mfma_f32_16x16x32_bf16 v[122:125], v[158:161], v[182:185], v[122:125]
	v_mfma_f32_16x16x32_bf16 v[110:113], v[150:153], v[190:193], v[110:113]
	v_mfma_f32_16x16x32_bf16 v[106:109], v[158:161], v[190:193], v[106:109]
	v_mfma_f32_16x16x32_bf16 v[94:97], v[150:153], v[208:211], v[94:97]
	v_mfma_f32_16x16x32_bf16 v[90:93], v[158:161], v[208:211], v[90:93]
	v_mfma_f32_16x16x32_bf16 v[78:81], v[150:153], v[216:219], v[78:81]
	v_mfma_f32_16x16x32_bf16 v[74:77], v[158:161], v[216:219], v[74:77]
	s_setprio 0
	s_setprio 1
	v_mfma_f32_16x16x32_bf16 v[118:121], v[162:165], v[178:181], v[118:121]
	v_mfma_f32_16x16x32_bf16 v[114:117], v[170:173], v[178:181], v[114:117]
	v_mfma_f32_16x16x32_bf16 v[102:105], v[162:165], v[186:189], v[102:105]
	v_mfma_f32_16x16x32_bf16 v[98:101], v[170:173], v[186:189], v[98:101]
	v_mfma_f32_16x16x32_bf16 v[86:89], v[162:165], v[204:207], v[86:89]
	v_mfma_f32_16x16x32_bf16 v[82:85], v[170:173], v[204:207], v[82:85]
	v_mfma_f32_16x16x32_bf16 v[70:73], v[162:165], v[212:215], v[70:73]
	v_mfma_f32_16x16x32_bf16 v[66:69], v[170:173], v[212:215], v[66:69]
	v_mfma_f32_16x16x32_bf16 v[118:121], v[166:169], v[182:185], v[118:121]
	v_mfma_f32_16x16x32_bf16 v[114:117], v[174:177], v[182:185], v[114:117]
	v_mfma_f32_16x16x32_bf16 v[102:105], v[166:169], v[190:193], v[102:105]
	v_mfma_f32_16x16x32_bf16 v[98:101], v[174:177], v[190:193], v[98:101]
	v_mfma_f32_16x16x32_bf16 v[86:89], v[166:169], v[208:211], v[86:89]
	v_mfma_f32_16x16x32_bf16 v[82:85], v[174:177], v[208:211], v[82:85]
	v_mfma_f32_16x16x32_bf16 v[70:73], v[166:169], v[216:219], v[70:73]
	v_mfma_f32_16x16x32_bf16 v[66:69], v[174:177], v[216:219], v[66:69]
	s_barrier
	s_setprio 0
	s_add_i32 s42, s42, s12
	s_mov_b32 m0, s42
	ds_read_b128 v[178:181], v145 offset:16384
	ds_read_b128 v[182:185], v145 offset:17408
	ds_read_b128 v[186:189], v145 offset:18432
	ds_read_b128 v[190:193], v145 offset:19456
	ds_read_b128 v[204:207], v145 offset:20480
	ds_read_b128 v[208:211], v145 offset:21504
	ds_read_b128 v[212:215], v145 offset:22528
	ds_read_b128 v[216:219], v145 offset:23552
	global_load_lds_dwordx4 v0, s[20:21]
	s_add_i32 m0, s42, 0x2000
	s_add_u32 s42, s20, 0x40000
	s_addc_u32 s43, s21, 0
	s_add_i32 s44, s44, s12
	global_load_lds_dwordx4 v130, s[20:21]
	s_mov_b32 m0, s44
	s_nop 0
	global_load_lds_dwordx4 v0, s[42:43]
	s_add_i32 m0, s44, 0x2000
	s_nop 0
	global_load_lds_dwordx4 v130, s[42:43]
	s_mov_b32 m0, s23
	s_nop 0
	global_load_lds_dwordx4 v134, s[60:61]
	s_mov_b32 m0, s24
	s_nop 0
	global_load_lds_dwordx4 v132, s[60:61]
	s_waitcnt vmcnt(8)
	s_waitcnt lgkmcnt(0)
	s_setprio 1
	s_barrier
	v_mfma_f32_16x16x32_bf16 v[62:65], v[146:149], v[178:181], v[62:65]
	v_mfma_f32_16x16x32_bf16 v[58:61], v[154:157], v[178:181], v[58:61]
	v_mfma_f32_16x16x32_bf16 v[46:49], v[146:149], v[186:189], v[46:49]
	v_mfma_f32_16x16x32_bf16 v[42:45], v[154:157], v[186:189], v[42:45]
	v_mfma_f32_16x16x32_bf16 v[30:33], v[146:149], v[204:207], v[30:33]
	v_mfma_f32_16x16x32_bf16 v[26:29], v[154:157], v[204:207], v[26:29]
	v_mfma_f32_16x16x32_bf16 v[14:17], v[146:149], v[212:215], v[14:17]
	v_mfma_f32_16x16x32_bf16 v[10:13], v[154:157], v[212:215], v[10:13]
	v_mfma_f32_16x16x32_bf16 v[62:65], v[150:153], v[182:185], v[62:65]
	v_mfma_f32_16x16x32_bf16 v[58:61], v[158:161], v[182:185], v[58:61]
	v_mfma_f32_16x16x32_bf16 v[46:49], v[150:153], v[190:193], v[46:49]
	v_mfma_f32_16x16x32_bf16 v[42:45], v[158:161], v[190:193], v[42:45]
	v_mfma_f32_16x16x32_bf16 v[30:33], v[150:153], v[208:211], v[30:33]
	v_mfma_f32_16x16x32_bf16 v[26:29], v[158:161], v[208:211], v[26:29]
	v_mfma_f32_16x16x32_bf16 v[14:17], v[150:153], v[216:219], v[14:17]
	v_mfma_f32_16x16x32_bf16 v[10:13], v[158:161], v[216:219], v[10:13]
	s_setprio 0
	s_setprio 1
	v_mfma_f32_16x16x32_bf16 v[54:57], v[162:165], v[178:181], v[54:57]
	v_mfma_f32_16x16x32_bf16 v[50:53], v[170:173], v[178:181], v[50:53]
	v_mfma_f32_16x16x32_bf16 v[38:41], v[162:165], v[186:189], v[38:41]
	v_mfma_f32_16x16x32_bf16 v[34:37], v[170:173], v[186:189], v[34:37]
	v_mfma_f32_16x16x32_bf16 v[22:25], v[162:165], v[204:207], v[22:25]
	v_mfma_f32_16x16x32_bf16 v[18:21], v[170:173], v[204:207], v[18:21]
	v_mfma_f32_16x16x32_bf16 v[6:9], v[162:165], v[212:215], v[6:9]
	v_mfma_f32_16x16x32_bf16 v[2:5], v[170:173], v[212:215], v[2:5]
	v_mfma_f32_16x16x32_bf16 v[54:57], v[166:169], v[182:185], v[54:57]
	v_mfma_f32_16x16x32_bf16 v[50:53], v[174:177], v[182:185], v[50:53]
	v_mfma_f32_16x16x32_bf16 v[38:41], v[166:169], v[190:193], v[38:41]
	v_mfma_f32_16x16x32_bf16 v[34:37], v[174:177], v[190:193], v[34:37]
	v_mfma_f32_16x16x32_bf16 v[22:25], v[166:169], v[208:211], v[22:25]
	v_mfma_f32_16x16x32_bf16 v[18:21], v[174:177], v[208:211], v[18:21]
	v_mfma_f32_16x16x32_bf16 v[6:9], v[166:169], v[216:219], v[6:9]
	v_mfma_f32_16x16x32_bf16 v[2:5], v[174:177], v[216:219], v[2:5]
	s_barrier
; #define PG8_STAGE(bufoff, gbase, voff) do { _Pragma("unroll") for (int _i = 0; _i < 2; ++_i) \
;         __builtin_amdgcn_global_load_lds((const gunsigned*)((const gchar*)(gbase) + (voff)[_i]), (LAS unsigned*)(lds + (bufoff) + ldsw + _i * 8192), 16, 0, 0); } while (0)
; #define PG8_LDA(dst, b, h) do { _Pragma("unroll") for (int m = 0; m < 4; ++m) _Pragma("unroll") for (int k = 0; k < 2; ++k) dst[m][k] = *(const LAS bf16x8*)(lds + PG8_SA(b, h) + aoff + m * 2048 + k * 1024); } while (0)
; #define PG8_LDB(dst, b, h) do { _Pragma("unroll") for (int n = 0; n < 2; ++n) _Pragma("unroll") for (int k = 0; k < 2; ++k) dst[n][k] = *(const LAS bf16x8*)(lds + PG8_SB(b, h) + boff + n * 2048 + k * 1024); } while (0)
; #define PG8_MMA(ai, bj, At, Bt) do { __builtin_amdgcn_s_setprio(1); _Pragma("unroll") for (int m = 0; m < 4; ++m) _Pragma("unroll") for (int n = 0; n < 2; ++n) _Pragma("unroll") for (int k = 0; k < 2; ++k) \
;         acc[ai][bj][m][n] = __builtin_amdgcn_mfma_f32_16x16x32_bf16(Bt[n][k], At[m][k], acc[ai][bj][m][n], 0, 0, 0); __builtin_amdgcn_s_setprio(0); } while (0)
; #define PG8_WAIT_V(n) asm volatile("s_waitcnt vmcnt(" #n ")" ::: "memory")
; #define PG8_WAIT_L(n) asm volatile("s_waitcnt lgkmcnt(" #n ")" ::: "memory")
; #define PG8_BAR __builtin_amdgcn_s_barrier()
; #define PG8_SCHED __builtin_amdgcn_sched_barrier(0)
; template <class Epi, class Sched>
; __device__ __forceinline__ void gemm_phase(LAS unsigned char* lds, const int tid, const Gemm g, const Sched& S, const Epi& E) {
;     ...
;             PG8_LDB(B0, 1, 0); PG8_LDB(B1, 1, 1); PG8_SCHED; PG8_LDA(At, 1, 0); PG8_STAGE(PG8_SA(0, 1), a2 + hstep, voffA);
;             PG8_WAIT_V(8); PG8_WAIT_L(0); PG8_BAR; PG8_MMA(0, 0, At, B0); PG8_MMA(0, 1, At, B1); PG8_BAR; PG8_SCHED;
;             PG8_LDA(At, 1, 1); PG8_STAGE(PG8_SB(1, 0), b3, voffB); PG8_STAGE(PG8_SB(1, 1), b3 + hstep, voffB); PG8_STAGE(PG8_SA(1, 0), a3, voffA);
;             PG8_WAIT_V(8); PG8_WAIT_L(0); PG8_BAR; PG8_MMA(1, 0, At, B0); PG8_MMA(1, 1, At, B1); PG8_BAR; PG8_SCHED;
;         }
;         if (wr == 0) PG8_BAR;
	s_setprio 0
	s_add_i32 s44, 0, 0x18000
	s_add_i32 s45, 0, 0x1c000
	v_add_u32_e32 v158, s44, v143
	v_add_u32_e32 v174, s45, v143
	ds_read_b128 v[146:149], v158
	ds_read_b128 v[150:153], v158 offset:1024
	ds_read_b128 v[154:157], v158 offset:2048
	ds_read_b128 v[158:161], v158 offset:3072
	ds_read_b128 v[162:165], v174
	ds_read_b128 v[166:169], v174 offset:1024
	ds_read_b128 v[170:173], v174 offset:2048
	ds_read_b128 v[174:177], v174 offset:3072
	s_add_u32 s42, s60, 0x40000
	s_addc_u32 s43, s61, 0
	s_mov_b32 m0, s29
	ds_read_b128 v[178:181], v145 offset:32768
	ds_read_b128 v[182:185], v145 offset:33792
	ds_read_b128 v[186:189], v145 offset:34816
	ds_read_b128 v[190:193], v145 offset:35840
	ds_read_b128 v[204:207], v145 offset:36864
	ds_read_b128 v[208:211], v145 offset:37888
	ds_read_b128 v[212:215], v145 offset:38912
	ds_read_b128 v[216:219], v145 offset:39936
	global_load_lds_dwordx4 v134, s[42:43]
	s_mov_b32 m0, s30
	s_nop 0
	global_load_lds_dwordx4 v132, s[42:43]
	s_waitcnt vmcnt(8)
	s_waitcnt lgkmcnt(0)
	s_setprio 1
	s_barrier
	v_mfma_f32_16x16x32_bf16 v[126:129], v[146:149], v[178:181], v[126:129]
	v_mfma_f32_16x16x32_bf16 v[122:125], v[154:157], v[178:181], v[122:125]
	v_mfma_f32_16x16x32_bf16 v[110:113], v[146:149], v[186:189], v[110:113]
	v_mfma_f32_16x16x32_bf16 v[106:109], v[154:157], v[186:189], v[106:109]
	v_mfma_f32_16x16x32_bf16 v[94:97], v[146:149], v[204:207], v[94:97]
	v_mfma_f32_16x16x32_bf16 v[90:93], v[154:157], v[204:207], v[90:93]
	v_mfma_f32_16x16x32_bf16 v[78:81], v[146:149], v[212:215], v[78:81]
	v_mfma_f32_16x16x32_bf16 v[74:77], v[154:157], v[212:215], v[74:77]
	v_mfma_f32_16x16x32_bf16 v[126:129], v[150:153], v[182:185], v[126:129]
	v_mfma_f32_16x16x32_bf16 v[122:125], v[158:161], v[182:185], v[122:125]
	v_mfma_f32_16x16x32_bf16 v[110:113], v[150:153], v[190:193], v[110:113]
	v_mfma_f32_16x16x32_bf16 v[106:109], v[158:161], v[190:193], v[106:109]
	v_mfma_f32_16x16x32_bf16 v[94:97], v[150:153], v[208:211], v[94:97]
	v_mfma_f32_16x16x32_bf16 v[90:93], v[158:161], v[208:211], v[90:93]
	v_mfma_f32_16x16x32_bf16 v[78:81], v[150:153], v[216:219], v[78:81]
	v_mfma_f32_16x16x32_bf16 v[74:77], v[158:161], v[216:219], v[74:77]
	s_setprio 0
	s_setprio 1
	v_mfma_f32_16x16x32_bf16 v[118:121], v[162:165], v[178:181], v[118:121]
	v_mfma_f32_16x16x32_bf16 v[114:117], v[170:173], v[178:181], v[114:117]
	v_mfma_f32_16x16x32_bf16 v[102:105], v[162:165], v[186:189], v[102:105]
	v_mfma_f32_16x16x32_bf16 v[98:101], v[170:173], v[186:189], v[98:101]
	v_mfma_f32_16x16x32_bf16 v[86:89], v[162:165], v[204:207], v[86:89]
	v_mfma_f32_16x16x32_bf16 v[82:85], v[170:173], v[204:207], v[82:85]
	v_mfma_f32_16x16x32_bf16 v[70:73], v[162:165], v[212:215], v[70:73]
	v_mfma_f32_16x16x32_bf16 v[66:69], v[170:173], v[212:215], v[66:69]
	v_mfma_f32_16x16x32_bf16 v[118:121], v[166:169], v[182:185], v[118:121]
	v_mfma_f32_16x16x32_bf16 v[114:117], v[174:177], v[182:185], v[114:117]
	v_mfma_f32_16x16x32_bf16 v[102:105], v[166:169], v[190:193], v[102:105]
	v_mfma_f32_16x16x32_bf16 v[98:101], v[174:177], v[190:193], v[98:101]
	v_mfma_f32_16x16x32_bf16 v[86:89], v[166:169], v[208:211], v[86:89]
	v_mfma_f32_16x16x32_bf16 v[82:85], v[174:177], v[208:211], v[82:85]
	v_mfma_f32_16x16x32_bf16 v[70:73], v[166:169], v[216:219], v[70:73]
	v_mfma_f32_16x16x32_bf16 v[66:69], v[174:177], v[216:219], v[66:69]
	s_barrier
	s_setprio 0
	s_add_i32 s42, s44, s12
	s_mov_b32 m0, s42
	ds_read_b128 v[178:181], v145 offset:49152
	ds_read_b128 v[182:185], v145 offset:50176
	ds_read_b128 v[186:189], v145 offset:51200
	ds_read_b128 v[190:193], v145 offset:52224
	ds_read_b128 v[204:207], v145 offset:53248
	ds_read_b128 v[208:211], v145 offset:54272
	ds_read_b128 v[212:215], v145 offset:55296
	ds_read_b128 v[216:219], v145 offset:56320
	global_load_lds_dwordx4 v141, s[20:21]
	s_add_i32 m0, s42, 0x2000
	s_add_i32 s42, s45, s12
	global_load_lds_dwordx4 v195, s[20:21]
	s_add_u32 s20, s20, 0x40080
	s_addc_u32 s21, s21, 0
	s_mov_b32 m0, s42
	s_nop 0
	global_load_lds_dwordx4 v0, s[20:21]
	s_add_i32 m0, s42, 0x2000
	s_nop 0
	global_load_lds_dwordx4 v130, s[20:21]
	s_mov_b32 m0, s31
	s_nop 0
	global_load_lds_dwordx4 v221, s[60:61]
	s_mov_b32 m0, s34
	s_nop 0
	global_load_lds_dwordx4 v223, s[60:61]
	s_waitcnt vmcnt(8)
	s_waitcnt lgkmcnt(0)
	s_setprio 1
	s_barrier
	v_mfma_f32_16x16x32_bf16 v[62:65], v[146:149], v[178:181], v[62:65]
	v_mfma_f32_16x16x32_bf16 v[58:61], v[154:157], v[178:181], v[58:61]
	v_mfma_f32_16x16x32_bf16 v[46:49], v[146:149], v[186:189], v[46:49]
	v_mfma_f32_16x16x32_bf16 v[42:45], v[154:157], v[186:189], v[42:45]
	v_mfma_f32_16x16x32_bf16 v[30:33], v[146:149], v[204:207], v[30:33]
	v_mfma_f32_16x16x32_bf16 v[26:29], v[154:157], v[204:207], v[26:29]
	v_mfma_f32_16x16x32_bf16 v[14:17], v[146:149], v[212:215], v[14:17]
	v_mfma_f32_16x16x32_bf16 v[10:13], v[154:157], v[212:215], v[10:13]
	v_mfma_f32_16x16x32_bf16 v[62:65], v[150:153], v[182:185], v[62:65]
	v_mfma_f32_16x16x32_bf16 v[58:61], v[158:161], v[182:185], v[58:61]
	v_mfma_f32_16x16x32_bf16 v[46:49], v[150:153], v[190:193], v[46:49]
	v_mfma_f32_16x16x32_bf16 v[42:45], v[158:161], v[190:193], v[42:45]
	v_mfma_f32_16x16x32_bf16 v[30:33], v[150:153], v[208:211], v[30:33]
	v_mfma_f32_16x16x32_bf16 v[26:29], v[158:161], v[208:211], v[26:29]
	v_mfma_f32_16x16x32_bf16 v[14:17], v[150:153], v[216:219], v[14:17]
	v_mfma_f32_16x16x32_bf16 v[10:13], v[158:161], v[216:219], v[10:13]
	s_setprio 0
	s_setprio 1
	v_mfma_f32_16x16x32_bf16 v[54:57], v[162:165], v[178:181], v[54:57]
	v_mfma_f32_16x16x32_bf16 v[50:53], v[170:173], v[178:181], v[50:53]
	v_mfma_f32_16x16x32_bf16 v[38:41], v[162:165], v[186:189], v[38:41]
	v_mfma_f32_16x16x32_bf16 v[34:37], v[170:173], v[186:189], v[34:37]
	v_mfma_f32_16x16x32_bf16 v[22:25], v[162:165], v[204:207], v[22:25]
	v_mfma_f32_16x16x32_bf16 v[18:21], v[170:173], v[204:207], v[18:21]
	v_mfma_f32_16x16x32_bf16 v[6:9], v[162:165], v[212:215], v[6:9]
	v_mfma_f32_16x16x32_bf16 v[2:5], v[170:173], v[212:215], v[2:5]
	v_mfma_f32_16x16x32_bf16 v[54:57], v[166:169], v[182:185], v[54:57]
	v_mfma_f32_16x16x32_bf16 v[50:53], v[174:177], v[182:185], v[50:53]
	v_mfma_f32_16x16x32_bf16 v[38:41], v[166:169], v[190:193], v[38:41]
	v_mfma_f32_16x16x32_bf16 v[34:37], v[174:177], v[190:193], v[34:37]
	v_mfma_f32_16x16x32_bf16 v[22:25], v[166:169], v[208:211], v[22:25]
	v_mfma_f32_16x16x32_bf16 v[18:21], v[174:177], v[208:211], v[18:21]
	v_mfma_f32_16x16x32_bf16 v[6:9], v[166:169], v[216:219], v[6:9]
	v_mfma_f32_16x16x32_bf16 v[2:5], v[174:177], v[216:219], v[2:5]
	s_barrier
	s_setprio 0
	s_add_i32 s41, s41, 2
	s_add_u32 s39, s39, 0x100
	s_addc_u32 s40, s40, 0
	s_add_u32 s58, s58, 0x100
	s_addc_u32 s59, s59, 0
	s_cmp_gt_u32 s41, 13
	s_cbranch_scc0 .LBB0_647
	s_and_b64 vcc, exec, s[4:5]
	s_cbranch_vccz .LBB0_650
	s_and_b64 vcc, exec, s[2:3]
	s_cbranch_vccnz .LBB0_650
	s_barrier
; #define LAS __attribute__((address_space(3)))
; __device__ __forceinline__ unsigned pk2(float lo, float hi) { f32x2 v = {lo, hi}; bf16x2_t b = __builtin_convertvector(v, bf16x2_t); return __builtin_bit_cast(unsigned, b); }
; __device__ __forceinline__ float sigmoidf_(float x) { return __builtin_amdgcn_rcpf(1.0f + __builtin_amdgcn_exp2f(-x * LOG2E)); }
;     __device__ __forceinline__ void operator()(const f32x4 (&acc)[2][2][4][2], const Unit& u, int wr, int wc, int fr, int fq, LAS unsigned char* lds, int tid) const {
;         const int row0 = u.pm * BM + wr * 64 + fr, col0 = u.pn * HALF + wc * 32 + 8 * fq;
; #pragma unroll
;         for (int ai = 0; ai < 2; ++ai)
; #pragma unroll
;             for (int m = 0; m < 4; ++m) { gbf16* rowp = O + (size_t)(row0 + ai * HALF + m * 16) * FF + col0;
;                 float h[8];
; #pragma unroll
;                 for (int n = 0; n < 2; ++n)
; #pragma unroll
;                     for (int e = 0; e < 4; ++e) { const float g = acc[ai][0][m][n][e], uu = acc[ai][1][m][n][e]; h[n * 4 + e] = g * sigmoidf_(g) * uu; }
;                 u32x4 w; w.x = pk2(h[0], h[1]); w.y = pk2(h[2], h[3]); w.z = pk2(h[4], h[5]); w.w = pk2(h[6], h[7]);
;                 *(gu32x4*)rowp = w; }
.LBB0_650:
	v_mul_f32_e32 v140, 0xbfb8aa3b, v126
	v_exp_f32_e32 v140, v140
	v_mul_f32_e32 v141, 0xbfb8aa3b, v127
	v_exp_f32_e32 v141, v141
	v_mul_f32_e32 v147, 0xbfb8aa3b, v128
	v_add_f32_e32 v140, 1.0, v140
	v_rcp_f32_e32 v150, v140
	v_add_f32_e32 v140, 1.0, v141
	v_rcp_f32_e32 v151, v140
	v_exp_f32_e32 v147, v147
	v_lshl_or_b32 v148, s36, 7, v144
	v_lshl_add_u32 v146, s56, 8, v142
	v_pk_mul_f32 v[126:127], v[126:127], v[150:151]
	v_mul_f32_e32 v150, 0xbfb8aa3b, v129
	v_exp_f32_e32 v150, v150
	v_pk_mul_f32 v[118:119], v[126:127], v[118:119]
	v_add_f32_e32 v126, 1.0, v147
	v_mul_f32_e32 v147, 0xbfb8aa3b, v122
	v_add_f32_e32 v127, 1.0, v150
	v_rcp_f32_e32 v126, v126
	v_rcp_f32_e32 v127, v127
	v_exp_f32_e32 v147, v147
	v_mul_f32_e32 v150, 0xbfb8aa3b, v123
	v_exp_f32_e32 v150, v150
	v_pk_mul_f32 v[126:127], v[128:129], v[126:127]
	v_add_f32_e32 v128, 1.0, v147
	v_mul_f32_e32 v147, 0xbfb8aa3b, v124
	v_add_f32_e32 v129, 1.0, v150
	v_exp_f32_e32 v147, v147
	v_mul_f32_e32 v150, 0xbfb8aa3b, v125
	v_exp_f32_e32 v151, v150
	v_rcp_f32_e32 v128, v128
	v_add_f32_e32 v147, 1.0, v147
	v_rcp_f32_e32 v129, v129
	v_rcp_f32_e32 v150, v147
	v_add_f32_e32 v147, 1.0, v151
	v_rcp_f32_e32 v151, v147
	v_pk_mul_f32 v[122:123], v[122:123], v[128:129]
	v_pk_mul_f32 v[120:121], v[126:127], v[120:121]
	v_pk_mul_f32 v[122:123], v[122:123], v[114:115]
	v_pk_mul_f32 v[114:115], v[124:125], v[150:151]
	v_ashrrev_i32_e32 v149, 31, v148
	v_pk_mul_f32 v[124:125], v[114:115], v[116:117]
	v_cvt_pk_bf16_f32 v117, v120, v121
	v_mul_f32_e32 v120, 0xbfb8aa3b, v110
	v_mul_f32_e32 v121, 0xbfb8aa3b, v111
	v_exp_f32_e32 v120, v120
	v_exp_f32_e32 v121, v121
	v_mov_b64_e32 v[140:141], s[88:89]
	v_mad_i64_i32 v[152:153], s[20:21], v146, s79, v[140:141]
	v_lshlrev_b64 v[114:115], 1, v[148:149]
	v_lshl_add_u64 v[126:127], v[152:153], 0, v[114:115]
	v_cvt_pk_bf16_f32 v116, v118, v119
	v_cvt_pk_bf16_f32 v118, v122, v123
	v_cvt_pk_bf16_f32 v119, v124, v125
	global_store_dwordx4 v[126:127], v[116:119], off
	s_andn2_b64 vcc, exec, s[2:3]
	s_mov_b64 s[2:3], -1
	v_add_f32_e32 v116, 1.0, v120
	v_add_f32_e32 v117, 1.0, v121
	v_rcp_f32_e32 v116, v116
	v_rcp_f32_e32 v117, v117
	v_or_b32_e32 v118, 16, v146
	v_mad_i64_i32 v[118:119], s[20:21], v118, s79, v[140:141]
	v_pk_mul_f32 v[110:111], v[110:111], v[116:117]
	v_mul_f32_e32 v116, 0xbfb8aa3b, v112
	v_mul_f32_e32 v117, 0xbfb8aa3b, v113
	v_exp_f32_e32 v116, v116
	v_exp_f32_e32 v117, v117
	v_pk_mul_f32 v[102:103], v[110:111], v[102:103]
	v_add_f32_e32 v110, 1.0, v116
	v_add_f32_e32 v111, 1.0, v117
	v_mul_f32_e32 v116, 0xbfb8aa3b, v106
	v_mul_f32_e32 v117, 0xbfb8aa3b, v107
	v_rcp_f32_e32 v110, v110
	v_rcp_f32_e32 v111, v111
	v_exp_f32_e32 v116, v116
	v_exp_f32_e32 v117, v117
	v_pk_mul_f32 v[110:111], v[112:113], v[110:111]
	v_add_f32_e32 v112, 1.0, v116
	v_add_f32_e32 v113, 1.0, v117
	v_mul_f32_e32 v116, 0xbfb8aa3b, v108
	v_mul_f32_e32 v117, 0xbfb8aa3b, v109
	v_exp_f32_e32 v116, v116
	v_exp_f32_e32 v117, v117
	v_rcp_f32_e32 v112, v112
	v_rcp_f32_e32 v113, v113
	v_add_f32_e32 v116, 1.0, v116
	v_add_f32_e32 v117, 1.0, v117
	v_rcp_f32_e32 v116, v116
	v_rcp_f32_e32 v117, v117
	v_pk_mul_f32 v[106:107], v[106:107], v[112:113]
	v_pk_mul_f32 v[104:105], v[110:111], v[104:105]
	v_pk_mul_f32 v[106:107], v[106:107], v[98:99]
	v_pk_mul_f32 v[98:99], v[108:109], v[116:117]
	v_lshl_add_u64 v[110:111], v[118:119], 0, v[114:115]
	v_pk_mul_f32 v[108:109], v[98:99], v[100:101]
	v_cvt_pk_bf16_f32 v98, v102, v103
	v_mul_f32_e32 v102, 0xbfb8aa3b, v94
	v_mul_f32_e32 v103, 0xbfb8aa3b, v95
	v_exp_f32_e32 v102, v102
	v_exp_f32_e32 v103, v103
	v_cvt_pk_bf16_f32 v99, v104, v105
	v_cvt_pk_bf16_f32 v100, v106, v107
	v_cvt_pk_bf16_f32 v101, v108, v109
	global_store_dwordx4 v[110:111], v[98:101], off
	s_nop 1
	v_add_f32_e32 v98, 1.0, v102
	v_add_f32_e32 v99, 1.0, v103
	v_rcp_f32_e32 v98, v98
	v_rcp_f32_e32 v99, v99
	v_or_b32_e32 v100, 32, v146
	v_mad_i64_i32 v[100:101], s[20:21], v100, s79, v[140:141]
	v_pk_mul_f32 v[94:95], v[94:95], v[98:99]
	v_mul_f32_e32 v98, 0xbfb8aa3b, v96
	v_mul_f32_e32 v99, 0xbfb8aa3b, v97
	v_exp_f32_e32 v98, v98
	v_exp_f32_e32 v99, v99
	v_pk_mul_f32 v[86:87], v[94:95], v[86:87]
	v_add_f32_e32 v94, 1.0, v98
	v_add_f32_e32 v95, 1.0, v99
	v_mul_f32_e32 v98, 0xbfb8aa3b, v90
	v_mul_f32_e32 v99, 0xbfb8aa3b, v91
	v_rcp_f32_e32 v94, v94
	v_rcp_f32_e32 v95, v95
	v_exp_f32_e32 v98, v98
	v_exp_f32_e32 v99, v99
	v_pk_mul_f32 v[94:95], v[96:97], v[94:95]
	v_add_f32_e32 v96, 1.0, v98
	v_add_f32_e32 v97, 1.0, v99
	v_mul_f32_e32 v98, 0xbfb8aa3b, v92
	v_mul_f32_e32 v99, 0xbfb8aa3b, v93
	v_exp_f32_e32 v98, v98
	v_exp_f32_e32 v99, v99
	v_rcp_f32_e32 v96, v96
	v_rcp_f32_e32 v97, v97
	v_add_f32_e32 v98, 1.0, v98
	v_add_f32_e32 v99, 1.0, v99
	v_rcp_f32_e32 v98, v98
	v_rcp_f32_e32 v99, v99
	v_pk_mul_f32 v[90:91], v[90:91], v[96:97]
	v_pk_mul_f32 v[88:89], v[94:95], v[88:89]
	v_pk_mul_f32 v[90:91], v[90:91], v[82:83]
	v_pk_mul_f32 v[82:83], v[92:93], v[98:99]
	v_lshl_add_u64 v[94:95], v[100:101], 0, v[114:115]
	v_pk_mul_f32 v[92:93], v[82:83], v[84:85]
	v_cvt_pk_bf16_f32 v82, v86, v87
	v_mul_f32_e32 v86, 0xbfb8aa3b, v78
	v_mul_f32_e32 v87, 0xbfb8aa3b, v79
	v_exp_f32_e32 v86, v86
	v_exp_f32_e32 v87, v87
	v_cvt_pk_bf16_f32 v83, v88, v89
	v_cvt_pk_bf16_f32 v84, v90, v91
	v_cvt_pk_bf16_f32 v85, v92, v93
	global_store_dwordx4 v[94:95], v[82:85], off
	s_nop 1
	v_add_f32_e32 v82, 1.0, v86
	v_add_f32_e32 v83, 1.0, v87
	v_rcp_f32_e32 v82, v82
	v_rcp_f32_e32 v83, v83
	v_or_b32_e32 v84, 48, v146
	v_mad_i64_i32 v[84:85], s[20:21], v84, s79, v[140:141]
	v_pk_mul_f32 v[78:79], v[78:79], v[82:83]
	v_mul_f32_e32 v82, 0xbfb8aa3b, v80
	v_mul_f32_e32 v83, 0xbfb8aa3b, v81
	v_exp_f32_e32 v82, v82
; __device__ __forceinline__ unsigned pk2(float lo, float hi) { f32x2 v = {lo, hi}; bf16x2_t b = __builtin_convertvector(v, bf16x2_t); return __builtin_bit_cast(unsigned, b); }
; __device__ __forceinline__ float sigmoidf_(float x) { return __builtin_amdgcn_rcpf(1.0f + __builtin_amdgcn_exp2f(-x * LOG2E)); }
;     __device__ __forceinline__ void operator()(const f32x4 (&acc)[2][2][4][2], const Unit& u, int wr, int wc, int fr, int fq, LAS unsigned char* lds, int tid) const {
;     ...
;         for (int ai = 0; ai < 2; ++ai)
; #pragma unroll
;             for (int m = 0; m < 4; ++m) { gbf16* rowp = O + (size_t)(row0 + ai * HALF + m * 16) * FF + col0;
;                 float h[8];
; #pragma unroll
;                 for (int n = 0; n < 2; ++n)
; #pragma unroll
;                     for (int e = 0; e < 4; ++e) { const float g = acc[ai][0][m][n][e], uu = acc[ai][1][m][n][e]; h[n * 4 + e] = g * sigmoidf_(g) * uu; }
;                 u32x4 w; w.x = pk2(h[0], h[1]); w.y = pk2(h[2], h[3]); w.z = pk2(h[4], h[5]); w.w = pk2(h[6], h[7]);
;                 *(gu32x4*)rowp = w; }
	v_exp_f32_e32 v83, v83
	v_pk_mul_f32 v[70:71], v[78:79], v[70:71]
	v_add_f32_e32 v78, 1.0, v82
	v_add_f32_e32 v79, 1.0, v83
	v_mul_f32_e32 v82, 0xbfb8aa3b, v74
	v_mul_f32_e32 v83, 0xbfb8aa3b, v75
	v_rcp_f32_e32 v78, v78
	v_rcp_f32_e32 v79, v79
	v_exp_f32_e32 v82, v82
	v_exp_f32_e32 v83, v83
	v_pk_mul_f32 v[78:79], v[80:81], v[78:79]
	v_add_f32_e32 v80, 1.0, v82
	v_add_f32_e32 v81, 1.0, v83
	v_mul_f32_e32 v82, 0xbfb8aa3b, v76
	v_mul_f32_e32 v83, 0xbfb8aa3b, v77
	v_exp_f32_e32 v82, v82
	v_exp_f32_e32 v83, v83
	v_rcp_f32_e32 v80, v80
	v_rcp_f32_e32 v81, v81
	v_add_f32_e32 v82, 1.0, v82
	v_add_f32_e32 v83, 1.0, v83
	v_rcp_f32_e32 v82, v82
	v_rcp_f32_e32 v83, v83
	v_pk_mul_f32 v[74:75], v[74:75], v[80:81]
	v_pk_mul_f32 v[72:73], v[78:79], v[72:73]
	v_pk_mul_f32 v[74:75], v[74:75], v[66:67]
	v_pk_mul_f32 v[66:67], v[76:77], v[82:83]
	v_lshl_add_u64 v[78:79], v[84:85], 0, v[114:115]
	v_pk_mul_f32 v[76:77], v[66:67], v[68:69]
	v_cvt_pk_bf16_f32 v66, v70, v71
	v_mul_f32_e32 v70, 0xbfb8aa3b, v62
	v_mul_f32_e32 v71, 0xbfb8aa3b, v63
	v_exp_f32_e32 v70, v70
	v_exp_f32_e32 v71, v71
	v_cvt_pk_bf16_f32 v67, v72, v73
	v_cvt_pk_bf16_f32 v68, v74, v75
	v_cvt_pk_bf16_f32 v69, v76, v77
	global_store_dwordx4 v[78:79], v[66:69], off
	s_nop 1
	v_add_f32_e32 v66, 1.0, v70
	v_add_f32_e32 v67, 1.0, v71
	v_rcp_f32_e32 v66, v66
	v_rcp_f32_e32 v67, v67
	v_add_u32_e32 v68, 0x80, v146
	v_mad_i64_i32 v[68:69], s[20:21], v68, s79, v[140:141]
	v_pk_mul_f32 v[62:63], v[62:63], v[66:67]
	v_mul_f32_e32 v66, 0xbfb8aa3b, v64
	v_mul_f32_e32 v67, 0xbfb8aa3b, v65
	v_exp_f32_e32 v66, v66
	v_exp_f32_e32 v67, v67
	v_pk_mul_f32 v[54:55], v[62:63], v[54:55]
	v_add_f32_e32 v62, 1.0, v66
	v_add_f32_e32 v63, 1.0, v67
	v_mul_f32_e32 v66, 0xbfb8aa3b, v58
	v_mul_f32_e32 v67, 0xbfb8aa3b, v59
	v_rcp_f32_e32 v62, v62
	v_rcp_f32_e32 v63, v63
	v_exp_f32_e32 v66, v66
	v_exp_f32_e32 v67, v67
	v_pk_mul_f32 v[62:63], v[64:65], v[62:63]
	v_add_f32_e32 v64, 1.0, v66
	v_add_f32_e32 v65, 1.0, v67
	v_mul_f32_e32 v66, 0xbfb8aa3b, v60
	v_mul_f32_e32 v67, 0xbfb8aa3b, v61
	v_exp_f32_e32 v66, v66
	v_exp_f32_e32 v67, v67
	v_rcp_f32_e32 v64, v64
	v_rcp_f32_e32 v65, v65
	v_add_f32_e32 v66, 1.0, v66
	v_add_f32_e32 v67, 1.0, v67
	v_rcp_f32_e32 v66, v66
	v_rcp_f32_e32 v67, v67
	v_pk_mul_f32 v[58:59], v[58:59], v[64:65]
	v_pk_mul_f32 v[56:57], v[62:63], v[56:57]
	v_pk_mul_f32 v[58:59], v[58:59], v[50:51]
	v_pk_mul_f32 v[50:51], v[60:61], v[66:67]
	v_lshl_add_u64 v[62:63], v[68:69], 0, v[114:115]
	v_pk_mul_f32 v[60:61], v[50:51], v[52:53]
	v_cvt_pk_bf16_f32 v50, v54, v55
	v_mul_f32_e32 v54, 0xbfb8aa3b, v46
	v_mul_f32_e32 v55, 0xbfb8aa3b, v47
	v_exp_f32_e32 v54, v54
	v_exp_f32_e32 v55, v55
	v_cvt_pk_bf16_f32 v51, v56, v57
	v_cvt_pk_bf16_f32 v52, v58, v59
	v_cvt_pk_bf16_f32 v53, v60, v61
	global_store_dwordx4 v[62:63], v[50:53], off
	s_nop 1
	v_add_f32_e32 v50, 1.0, v54
	v_add_f32_e32 v51, 1.0, v55
	v_rcp_f32_e32 v50, v50
	v_rcp_f32_e32 v51, v51
	v_add_u32_e32 v52, 0x90, v146
	v_mad_i64_i32 v[52:53], s[20:21], v52, s79, v[140:141]
	v_pk_mul_f32 v[46:47], v[46:47], v[50:51]
	v_mul_f32_e32 v50, 0xbfb8aa3b, v48
	v_mul_f32_e32 v51, 0xbfb8aa3b, v49
	v_exp_f32_e32 v50, v50
	v_exp_f32_e32 v51, v51
	v_pk_mul_f32 v[38:39], v[46:47], v[38:39]
	v_add_f32_e32 v46, 1.0, v50
	v_add_f32_e32 v47, 1.0, v51
	v_mul_f32_e32 v50, 0xbfb8aa3b, v42
	v_mul_f32_e32 v51, 0xbfb8aa3b, v43
	v_rcp_f32_e32 v46, v46
	v_rcp_f32_e32 v47, v47
	v_exp_f32_e32 v50, v50
	v_exp_f32_e32 v51, v51
	v_pk_mul_f32 v[46:47], v[48:49], v[46:47]
	v_add_f32_e32 v48, 1.0, v50
	v_add_f32_e32 v49, 1.0, v51
	v_mul_f32_e32 v50, 0xbfb8aa3b, v44
	v_mul_f32_e32 v51, 0xbfb8aa3b, v45
	v_exp_f32_e32 v50, v50
	v_exp_f32_e32 v51, v51
	v_rcp_f32_e32 v48, v48
	v_rcp_f32_e32 v49, v49
	v_add_f32_e32 v50, 1.0, v50
; __device__ __forceinline__ unsigned pk2(float lo, float hi) { f32x2 v = {lo, hi}; bf16x2_t b = __builtin_convertvector(v, bf16x2_t); return __builtin_bit_cast(unsigned, b); }
; __device__ __forceinline__ float sigmoidf_(float x) { return __builtin_amdgcn_rcpf(1.0f + __builtin_amdgcn_exp2f(-x * LOG2E)); }
; #define PG8_BAR __builtin_amdgcn_s_barrier()
;     __device__ __forceinline__ void operator()(const f32x4 (&acc)[2][2][4][2], const Unit& u, int wr, int wc, int fr, int fq, LAS unsigned char* lds, int tid) const {
;     ...
;         for (int ai = 0; ai < 2; ++ai)
; #pragma unroll
;             for (int m = 0; m < 4; ++m) { gbf16* rowp = O + (size_t)(row0 + ai * HALF + m * 16) * FF + col0;
;                 float h[8];
; #pragma unroll
;                 for (int n = 0; n < 2; ++n)
; #pragma unroll
;                     for (int e = 0; e < 4; ++e) { const float g = acc[ai][0][m][n][e], uu = acc[ai][1][m][n][e]; h[n * 4 + e] = g * sigmoidf_(g) * uu; }
;                 u32x4 w; w.x = pk2(h[0], h[1]); w.y = pk2(h[2], h[3]); w.z = pk2(h[4], h[5]); w.w = pk2(h[6], h[7]);
;                 *(gu32x4*)rowp = w; }
; template <class Epi, class Sched>
; __device__ __forceinline__ void gemm_phase(LAS unsigned char* lds, const int tid, const Gemm g, const Sched& S, const Epi& E) {
;     ...
;         if (!has_next) break;
; #pragma unroll
;         for (int a = 0; a < 2; ++a)
; #pragma unroll
;             for (int b = 0; b < 2; ++b)
; #pragma unroll
;                 for (int m = 0; m < 4; ++m)
; #pragma unroll
;                     for (int n = 0; n < 2; ++n) acc[a][b][m][n] = (f32x4){0.f, 0.f, 0.f, 0.f};
;         cur = nxt; cA = nA; cB = nB; ++ui;
;         if (wr == 1) PG8_BAR;
;     }
	v_add_f32_e32 v51, 1.0, v51
	v_rcp_f32_e32 v50, v50
	v_rcp_f32_e32 v51, v51
	v_pk_mul_f32 v[42:43], v[42:43], v[48:49]
	v_pk_mul_f32 v[40:41], v[46:47], v[40:41]
	v_pk_mul_f32 v[42:43], v[42:43], v[34:35]
	v_pk_mul_f32 v[34:35], v[44:45], v[50:51]
	v_lshl_add_u64 v[46:47], v[52:53], 0, v[114:115]
	v_pk_mul_f32 v[44:45], v[34:35], v[36:37]
	v_cvt_pk_bf16_f32 v34, v38, v39
	v_mul_f32_e32 v38, 0xbfb8aa3b, v30
	v_mul_f32_e32 v39, 0xbfb8aa3b, v31
	v_exp_f32_e32 v38, v38
	v_exp_f32_e32 v39, v39
	v_cvt_pk_bf16_f32 v35, v40, v41
	v_cvt_pk_bf16_f32 v36, v42, v43
	v_cvt_pk_bf16_f32 v37, v44, v45
	global_store_dwordx4 v[46:47], v[34:37], off
	s_nop 1
	v_add_f32_e32 v34, 1.0, v38
	v_add_f32_e32 v35, 1.0, v39
	v_rcp_f32_e32 v34, v34
	v_rcp_f32_e32 v35, v35
	v_add_u32_e32 v36, 0xa0, v146
	v_mad_i64_i32 v[36:37], s[20:21], v36, s79, v[140:141]
	v_pk_mul_f32 v[30:31], v[30:31], v[34:35]
	v_mul_f32_e32 v34, 0xbfb8aa3b, v32
	v_mul_f32_e32 v35, 0xbfb8aa3b, v33
	v_exp_f32_e32 v34, v34
	v_exp_f32_e32 v35, v35
	v_pk_mul_f32 v[22:23], v[30:31], v[22:23]
	v_add_f32_e32 v30, 1.0, v34
	v_add_f32_e32 v31, 1.0, v35
	v_mul_f32_e32 v34, 0xbfb8aa3b, v26
	v_mul_f32_e32 v35, 0xbfb8aa3b, v27
	v_rcp_f32_e32 v30, v30
	v_rcp_f32_e32 v31, v31
	v_exp_f32_e32 v34, v34
	v_exp_f32_e32 v35, v35
	v_pk_mul_f32 v[30:31], v[32:33], v[30:31]
	v_add_f32_e32 v32, 1.0, v34
	v_add_f32_e32 v33, 1.0, v35
	v_mul_f32_e32 v34, 0xbfb8aa3b, v28
	v_mul_f32_e32 v35, 0xbfb8aa3b, v29
	v_exp_f32_e32 v34, v34
	v_exp_f32_e32 v35, v35
	v_rcp_f32_e32 v32, v32
	v_rcp_f32_e32 v33, v33
	v_add_f32_e32 v34, 1.0, v34
	v_add_f32_e32 v35, 1.0, v35
	v_rcp_f32_e32 v34, v34
	v_rcp_f32_e32 v35, v35
	v_pk_mul_f32 v[26:27], v[26:27], v[32:33]
	v_pk_mul_f32 v[24:25], v[30:31], v[24:25]
	v_pk_mul_f32 v[26:27], v[26:27], v[18:19]
	v_pk_mul_f32 v[18:19], v[28:29], v[34:35]
	v_lshl_add_u64 v[30:31], v[36:37], 0, v[114:115]
	v_pk_mul_f32 v[28:29], v[18:19], v[20:21]
	v_cvt_pk_bf16_f32 v18, v22, v23
	v_mul_f32_e32 v22, 0xbfb8aa3b, v14
	v_mul_f32_e32 v23, 0xbfb8aa3b, v15
	v_exp_f32_e32 v22, v22
	v_exp_f32_e32 v23, v23
	v_cvt_pk_bf16_f32 v19, v24, v25
	v_cvt_pk_bf16_f32 v20, v26, v27
	v_cvt_pk_bf16_f32 v21, v28, v29
	global_store_dwordx4 v[30:31], v[18:21], off
	s_nop 1
	v_add_f32_e32 v18, 1.0, v22
	v_add_f32_e32 v19, 1.0, v23
	v_rcp_f32_e32 v18, v18
	v_rcp_f32_e32 v19, v19
	v_add_u32_e32 v20, 0xb0, v146
	v_mad_i64_i32 v[20:21], s[20:21], v20, s79, v[140:141]
	v_pk_mul_f32 v[14:15], v[14:15], v[18:19]
	v_mul_f32_e32 v18, 0xbfb8aa3b, v16
	v_mul_f32_e32 v19, 0xbfb8aa3b, v17
	v_exp_f32_e32 v18, v18
	v_exp_f32_e32 v19, v19
	v_pk_mul_f32 v[6:7], v[14:15], v[6:7]
	v_add_f32_e32 v14, 1.0, v18
	v_add_f32_e32 v15, 1.0, v19
	v_mul_f32_e32 v18, 0xbfb8aa3b, v10
	v_mul_f32_e32 v19, 0xbfb8aa3b, v11
	v_rcp_f32_e32 v14, v14
	v_rcp_f32_e32 v15, v15
	v_exp_f32_e32 v18, v18
	v_exp_f32_e32 v19, v19
	v_pk_mul_f32 v[14:15], v[16:17], v[14:15]
	v_add_f32_e32 v16, 1.0, v18
	v_add_f32_e32 v17, 1.0, v19
	v_mul_f32_e32 v18, 0xbfb8aa3b, v12
	v_mul_f32_e32 v19, 0xbfb8aa3b, v13
	v_exp_f32_e32 v18, v18
	v_exp_f32_e32 v19, v19
	v_rcp_f32_e32 v16, v16
	v_rcp_f32_e32 v17, v17
	v_add_f32_e32 v18, 1.0, v18
	v_add_f32_e32 v19, 1.0, v19
	v_rcp_f32_e32 v18, v18
	v_rcp_f32_e32 v19, v19
	v_pk_mul_f32 v[10:11], v[10:11], v[16:17]
	v_pk_mul_f32 v[8:9], v[14:15], v[8:9]
	v_pk_mul_f32 v[10:11], v[10:11], v[2:3]
	v_pk_mul_f32 v[2:3], v[12:13], v[18:19]
	v_lshl_add_u64 v[14:15], v[20:21], 0, v[114:115]
	v_pk_mul_f32 v[12:13], v[2:3], v[4:5]
	v_cvt_pk_bf16_f32 v2, v6, v7
	v_cvt_pk_bf16_f32 v3, v8, v9
	v_cvt_pk_bf16_f32 v4, v10, v11
	v_cvt_pk_bf16_f32 v5, v12, v13
	global_store_dwordx4 v[14:15], v[2:5], off
	s_cbranch_vccnz .LBB0_643
	s_andn2_b64 vcc, exec, s[0:1]
	s_cbranch_vccnz .LBB0_642
	s_branch .LBB0_642
